# k5 plus: first K-iteration of each GEMM unit skips the L1 vmcnt wait (needed pieces retired by a vmcnt(6) at loop exit before the epilogue stores), so the wait no longer drains the epilogue stores
# baseline (speedup 1.0000x reference)
.LBB0_670:
	ds_read_b128 v[154:157], v150
	ds_read_b128 v[158:161], v150 offset:1024
	ds_read_b128 v[162:165], v150 offset:2048
	ds_read_b128 v[166:169], v150 offset:3072
	ds_read_b128 v[202:205], v152
	ds_read_b128 v[206:209], v152 offset:1024
	ds_read_b128 v[210:213], v152 offset:2048
	ds_read_b128 v[214:217], v152 offset:3072
	s_add_u32 s28, s34, 0xfff00080
	s_addc_u32 s29, s35, -1
	s_cmp_eq_u32 s94, 60
	s_cselect_b32 s39, s23, s29
	s_cselect_b32 s38, s22, s28
	s_cselect_b32 s37, s21, s93
	s_cselect_b32 s36, s20, s19
	v_lshl_add_u64 v[146:147], s[34:35], 0, v[142:143]
	s_add_i32 m0, s27, 0xc000
	ds_read_b128 v[170:173], v151
	ds_read_b128 v[174:177], v151 offset:1024
	ds_read_b128 v[178:181], v151 offset:2048
	ds_read_b128 v[182:185], v151 offset:3072
	ds_read_b128 v[186:189], v151 offset:4096
	ds_read_b128 v[190:193], v151 offset:5120
	ds_read_b128 v[194:197], v151 offset:6144
	ds_read_b128 v[198:201], v151 offset:7168
	global_load_lds_dwordx4 v[146:147], off
	v_lshl_add_u64 v[146:147], s[34:35], 0, v[140:141]
	s_add_i32 m0, s27, 0xe000
	s_nop 0
	global_load_lds_dwordx4 v[146:147], off
	s_cmp_eq_u32 s94, -2
	s_cbranch_scc1 .Lk2_skip_670
	s_waitcnt vmcnt(8)
.Lk2_skip_670:
	s_waitcnt lgkmcnt(0)
	s_barrier
	s_setprio 1
	v_mfma_f32_16x16x32_bf16 v[126:129], v[154:157], v[170:173], v[126:129]
	v_mfma_f32_16x16x32_bf16 v[122:125], v[162:165], v[170:173], v[122:125]
	v_mfma_f32_16x16x32_bf16 v[118:121], v[154:157], v[178:181], v[118:121]
	v_mfma_f32_16x16x32_bf16 v[110:113], v[162:165], v[178:181], v[110:113]
	v_mfma_f32_16x16x32_bf16 v[102:105], v[154:157], v[186:189], v[102:105]
	v_mfma_f32_16x16x32_bf16 v[94:97], v[162:165], v[186:189], v[94:97]
	v_mfma_f32_16x16x32_bf16 v[86:89], v[154:157], v[194:197], v[86:89]
	v_mfma_f32_16x16x32_bf16 v[78:81], v[162:165], v[194:197], v[78:81]
	v_mfma_f32_16x16x32_bf16 v[126:129], v[158:161], v[174:177], v[126:129]
	v_mfma_f32_16x16x32_bf16 v[122:125], v[166:169], v[174:177], v[122:125]
	v_mfma_f32_16x16x32_bf16 v[118:121], v[158:161], v[182:185], v[118:121]
	v_mfma_f32_16x16x32_bf16 v[110:113], v[166:169], v[182:185], v[110:113]
	v_mfma_f32_16x16x32_bf16 v[102:105], v[158:161], v[190:193], v[102:105]
	v_mfma_f32_16x16x32_bf16 v[94:97], v[166:169], v[190:193], v[94:97]
	v_mfma_f32_16x16x32_bf16 v[86:89], v[158:161], v[198:201], v[86:89]
	v_mfma_f32_16x16x32_bf16 v[78:81], v[166:169], v[198:201], v[78:81]
	v_mfma_f32_16x16x32_bf16 v[114:117], v[202:205], v[170:173], v[114:117]
	v_mfma_f32_16x16x32_bf16 v[106:109], v[210:213], v[170:173], v[106:109]
	v_mfma_f32_16x16x32_bf16 v[98:101], v[202:205], v[178:181], v[98:101]
	v_mfma_f32_16x16x32_bf16 v[90:93], v[210:213], v[178:181], v[90:93]
	v_mfma_f32_16x16x32_bf16 v[82:85], v[202:205], v[186:189], v[82:85]
	v_mfma_f32_16x16x32_bf16 v[74:77], v[210:213], v[186:189], v[74:77]
	v_mfma_f32_16x16x32_bf16 v[70:73], v[202:205], v[194:197], v[70:73]
	v_mfma_f32_16x16x32_bf16 v[66:69], v[210:213], v[194:197], v[66:69]
	v_mfma_f32_16x16x32_bf16 v[114:117], v[206:209], v[174:177], v[114:117]
	v_mfma_f32_16x16x32_bf16 v[106:109], v[214:217], v[174:177], v[106:109]
	v_mfma_f32_16x16x32_bf16 v[98:101], v[206:209], v[182:185], v[98:101]
	v_mfma_f32_16x16x32_bf16 v[90:93], v[214:217], v[182:185], v[90:93]
	v_mfma_f32_16x16x32_bf16 v[82:85], v[206:209], v[190:193], v[82:85]
	v_mfma_f32_16x16x32_bf16 v[74:77], v[214:217], v[190:193], v[74:77]
	v_mfma_f32_16x16x32_bf16 v[70:73], v[206:209], v[198:201], v[70:73]
	v_mfma_f32_16x16x32_bf16 v[66:69], v[214:217], v[198:201], v[66:69]
	s_setprio 0
	s_barrier
	ds_read_b128 v[170:173], v151 offset:16384
	ds_read_b128 v[174:177], v151 offset:17408
	ds_read_b128 v[178:181], v151 offset:18432
	ds_read_b128 v[182:185], v151 offset:19456
	ds_read_b128 v[186:189], v151 offset:20480
	ds_read_b128 v[190:193], v151 offset:21504
	ds_read_b128 v[194:197], v151 offset:22528
	ds_read_b128 v[198:201], v151 offset:23552
	s_add_i32 s28, s85, s74
	v_lshl_add_u64 v[146:147], s[36:37], 0, v[134:135]
	s_mov_b32 m0, s28
	s_nop 0
	global_load_lds_dwordx4 v[146:147], off
	v_lshl_add_u64 v[218:219], s[36:37], 0, v[130:131]
	s_add_i32 m0, s28, 0x2000
	s_nop 0
	global_load_lds_dwordx4 v[218:219], off
	s_mov_b32 m0, s27
	v_lshl_add_u64 v[220:221], s[38:39], 0, v[136:137]
	global_load_lds_dwordx4 v[220:221], off
	v_lshl_add_u64 v[222:223], s[38:39], 0, v[132:133]
	s_mov_b32 m0, s76
	s_nop 0
	global_load_lds_dwordx4 v[222:223], off
	s_add_u32 s28, s36, 0x100000
	s_addc_u32 s29, s37, 0
	s_add_i32 s95, s86, s74
	v_lshl_add_u64 v[226:227], s[28:29], 0, v[134:135]
	s_mov_b32 m0, s95
	s_nop 0
	global_load_lds_dwordx4 v[226:227], off
	v_lshl_add_u64 v[226:227], s[28:29], 0, v[130:131]
	s_add_i32 m0, s95, 0x2000
	s_nop 0
	global_load_lds_dwordx4 v[226:227], off
	s_waitcnt vmcnt(8)
	s_waitcnt lgkmcnt(0)
	s_barrier
	s_setprio 1
	v_mfma_f32_16x16x32_bf16 v[62:65], v[154:157], v[170:173], v[62:65]
	v_mfma_f32_16x16x32_bf16 v[58:61], v[162:165], v[170:173], v[58:61]
	v_mfma_f32_16x16x32_bf16 v[54:57], v[154:157], v[178:181], v[54:57]
	v_mfma_f32_16x16x32_bf16 v[46:49], v[162:165], v[178:181], v[46:49]
	v_mfma_f32_16x16x32_bf16 v[38:41], v[154:157], v[186:189], v[38:41]
	v_mfma_f32_16x16x32_bf16 v[30:33], v[162:165], v[186:189], v[30:33]
	v_mfma_f32_16x16x32_bf16 v[22:25], v[154:157], v[194:197], v[22:25]
	v_mfma_f32_16x16x32_bf16 v[14:17], v[162:165], v[194:197], v[14:17]
	v_mfma_f32_16x16x32_bf16 v[62:65], v[158:161], v[174:177], v[62:65]
	v_mfma_f32_16x16x32_bf16 v[58:61], v[166:169], v[174:177], v[58:61]
	v_mfma_f32_16x16x32_bf16 v[54:57], v[158:161], v[182:185], v[54:57]
	v_mfma_f32_16x16x32_bf16 v[46:49], v[166:169], v[182:185], v[46:49]
	v_mfma_f32_16x16x32_bf16 v[38:41], v[158:161], v[190:193], v[38:41]
	v_mfma_f32_16x16x32_bf16 v[30:33], v[166:169], v[190:193], v[30:33]
	v_mfma_f32_16x16x32_bf16 v[22:25], v[158:161], v[198:201], v[22:25]
	v_mfma_f32_16x16x32_bf16 v[14:17], v[166:169], v[198:201], v[14:17]
	v_mfma_f32_16x16x32_bf16 v[50:53], v[202:205], v[170:173], v[50:53]
	v_mfma_f32_16x16x32_bf16 v[42:45], v[210:213], v[170:173], v[42:45]
	v_mfma_f32_16x16x32_bf16 v[34:37], v[202:205], v[178:181], v[34:37]
	v_mfma_f32_16x16x32_bf16 v[26:29], v[210:213], v[178:181], v[26:29]
	v_mfma_f32_16x16x32_bf16 v[18:21], v[202:205], v[186:189], v[18:21]
	v_mfma_f32_16x16x32_bf16 v[10:13], v[210:213], v[186:189], v[10:13]
	v_mfma_f32_16x16x32_bf16 v[6:9], v[202:205], v[194:197], v[6:9]
	v_mfma_f32_16x16x32_bf16 v[2:5], v[210:213], v[194:197], v[2:5]
	v_mfma_f32_16x16x32_bf16 v[50:53], v[206:209], v[174:177], v[50:53]
	v_mfma_f32_16x16x32_bf16 v[42:45], v[214:217], v[174:177], v[42:45]
	v_mfma_f32_16x16x32_bf16 v[34:37], v[206:209], v[182:185], v[34:37]
	v_mfma_f32_16x16x32_bf16 v[26:29], v[214:217], v[182:185], v[26:29]
	v_mfma_f32_16x16x32_bf16 v[18:21], v[206:209], v[190:193], v[18:21]
	v_mfma_f32_16x16x32_bf16 v[10:13], v[214:217], v[190:193], v[10:13]
	v_mfma_f32_16x16x32_bf16 v[6:9], v[206:209], v[198:201], v[6:9]
	v_mfma_f32_16x16x32_bf16 v[2:5], v[214:217], v[198:201], v[2:5]
	s_setprio 0
	s_add_i32 s95, 0, 0x18000
	v_add_u32_e32 v153, s95, v148
	s_barrier
	ds_read_b128 v[154:157], v153
	ds_read_b128 v[158:161], v153 offset:1024
	ds_read_b128 v[162:165], v153 offset:2048
	ds_read_b128 v[166:169], v153 offset:3072
	ds_read_b128 v[202:205], v153 offset:16384
	ds_read_b128 v[206:209], v153 offset:17408
	ds_read_b128 v[210:213], v153 offset:18432
	ds_read_b128 v[214:217], v153 offset:19456
	s_add_u32 s28, s38, 0x100000
	s_addc_u32 s29, s39, 0
	s_mov_b32 m0, s77
	v_lshl_add_u64 v[226:227], s[28:29], 0, v[136:137]
	ds_read_b128 v[170:173], v151 offset:32768
	ds_read_b128 v[174:177], v151 offset:33792
	ds_read_b128 v[178:181], v151 offset:34816
	ds_read_b128 v[182:185], v151 offset:35840
	ds_read_b128 v[186:189], v151 offset:36864
	ds_read_b128 v[190:193], v151 offset:37888
	ds_read_b128 v[194:197], v151 offset:38912
	ds_read_b128 v[198:201], v151 offset:39936
	global_load_lds_dwordx4 v[226:227], off
	v_lshl_add_u64 v[226:227], s[28:29], 0, v[132:133]
	s_mov_b32 m0, s78
	s_nop 0
	global_load_lds_dwordx4 v[226:227], off
	s_waitcnt vmcnt(8)
	s_waitcnt lgkmcnt(0)
	s_barrier
	s_setprio 1
	v_mfma_f32_16x16x32_bf16 v[126:129], v[154:157], v[170:173], v[126:129]
	v_mfma_f32_16x16x32_bf16 v[122:125], v[162:165], v[170:173], v[122:125]
	v_mfma_f32_16x16x32_bf16 v[118:121], v[154:157], v[178:181], v[118:121]
	v_mfma_f32_16x16x32_bf16 v[110:113], v[162:165], v[178:181], v[110:113]
	v_mfma_f32_16x16x32_bf16 v[102:105], v[154:157], v[186:189], v[102:105]
	v_mfma_f32_16x16x32_bf16 v[94:97], v[162:165], v[186:189], v[94:97]
	v_mfma_f32_16x16x32_bf16 v[86:89], v[154:157], v[194:197], v[86:89]
	v_mfma_f32_16x16x32_bf16 v[78:81], v[162:165], v[194:197], v[78:81]
	v_mfma_f32_16x16x32_bf16 v[126:129], v[158:161], v[174:177], v[126:129]
	v_mfma_f32_16x16x32_bf16 v[122:125], v[166:169], v[174:177], v[122:125]
	v_mfma_f32_16x16x32_bf16 v[118:121], v[158:161], v[182:185], v[118:121]
	v_mfma_f32_16x16x32_bf16 v[110:113], v[166:169], v[182:185], v[110:113]
	v_mfma_f32_16x16x32_bf16 v[102:105], v[158:161], v[190:193], v[102:105]
	v_mfma_f32_16x16x32_bf16 v[94:97], v[166:169], v[190:193], v[94:97]
	v_mfma_f32_16x16x32_bf16 v[86:89], v[158:161], v[198:201], v[86:89]
	v_mfma_f32_16x16x32_bf16 v[78:81], v[166:169], v[198:201], v[78:81]
	v_mfma_f32_16x16x32_bf16 v[114:117], v[202:205], v[170:173], v[114:117]
	v_mfma_f32_16x16x32_bf16 v[106:109], v[210:213], v[170:173], v[106:109]
	v_mfma_f32_16x16x32_bf16 v[98:101], v[202:205], v[178:181], v[98:101]
	v_mfma_f32_16x16x32_bf16 v[90:93], v[210:213], v[178:181], v[90:93]
	v_mfma_f32_16x16x32_bf16 v[82:85], v[202:205], v[186:189], v[82:85]
	v_mfma_f32_16x16x32_bf16 v[74:77], v[210:213], v[186:189], v[74:77]
	v_mfma_f32_16x16x32_bf16 v[70:73], v[202:205], v[194:197], v[70:73]
	v_mfma_f32_16x16x32_bf16 v[66:69], v[210:213], v[194:197], v[66:69]
	v_mfma_f32_16x16x32_bf16 v[114:117], v[206:209], v[174:177], v[114:117]
	v_mfma_f32_16x16x32_bf16 v[106:109], v[214:217], v[174:177], v[106:109]
	v_mfma_f32_16x16x32_bf16 v[98:101], v[206:209], v[182:185], v[98:101]
	v_mfma_f32_16x16x32_bf16 v[90:93], v[214:217], v[182:185], v[90:93]
	v_mfma_f32_16x16x32_bf16 v[82:85], v[206:209], v[190:193], v[82:85]
	v_mfma_f32_16x16x32_bf16 v[74:77], v[214:217], v[190:193], v[74:77]
	v_mfma_f32_16x16x32_bf16 v[70:73], v[206:209], v[198:201], v[70:73]
	v_mfma_f32_16x16x32_bf16 v[66:69], v[214:217], v[198:201], v[66:69]
	s_setprio 0
	s_barrier
	ds_read_b128 v[170:173], v151 offset:49152
	ds_read_b128 v[174:177], v151 offset:50176
	ds_read_b128 v[178:181], v151 offset:51200
	ds_read_b128 v[182:185], v151 offset:52224
	ds_read_b128 v[186:189], v151 offset:53248
	ds_read_b128 v[190:193], v151 offset:54272
	ds_read_b128 v[194:197], v151 offset:55296
	ds_read_b128 v[198:201], v151 offset:56320
	s_add_i32 s38, 0, 0x1c000
	s_add_i32 s28, s95, s74
	v_lshl_add_u64 v[146:147], v[146:147], 0, s[0:1]
	s_mov_b32 m0, s28
	s_nop 0
	global_load_lds_dwordx4 v[146:147], off
	v_lshl_add_u64 v[146:147], v[218:219], 0, s[0:1]
	s_add_i32 m0, s28, 0x2000
	s_nop 0
	global_load_lds_dwordx4 v[146:147], off
	s_mov_b32 m0, s80
	v_lshl_add_u64 v[146:147], v[220:221], 0, s[0:1]
	global_load_lds_dwordx4 v[146:147], off
	v_lshl_add_u64 v[146:147], v[222:223], 0, s[0:1]
	s_mov_b32 m0, s81
	s_nop 0
	global_load_lds_dwordx4 v[146:147], off
	s_add_u32 s28, s36, 0x100080
	s_addc_u32 s29, s37, 0
	s_add_i32 s36, s38, s74
	v_lshl_add_u64 v[146:147], s[28:29], 0, v[134:135]
	s_mov_b32 m0, s36
	s_nop 0
	global_load_lds_dwordx4 v[146:147], off
	v_lshl_add_u64 v[146:147], s[28:29], 0, v[130:131]
	s_add_i32 m0, s36, 0x2000
	s_nop 0
	global_load_lds_dwordx4 v[146:147], off
	s_waitcnt vmcnt(8)
	s_waitcnt lgkmcnt(0)
	s_barrier
	s_setprio 1
	v_mfma_f32_16x16x32_bf16 v[62:65], v[154:157], v[170:173], v[62:65]
	v_mfma_f32_16x16x32_bf16 v[58:61], v[162:165], v[170:173], v[58:61]
	v_mfma_f32_16x16x32_bf16 v[54:57], v[154:157], v[178:181], v[54:57]
	v_mfma_f32_16x16x32_bf16 v[46:49], v[162:165], v[178:181], v[46:49]
	v_mfma_f32_16x16x32_bf16 v[38:41], v[154:157], v[186:189], v[38:41]
	v_mfma_f32_16x16x32_bf16 v[30:33], v[162:165], v[186:189], v[30:33]
	v_mfma_f32_16x16x32_bf16 v[22:25], v[154:157], v[194:197], v[22:25]
	v_mfma_f32_16x16x32_bf16 v[14:17], v[162:165], v[194:197], v[14:17]
	v_mfma_f32_16x16x32_bf16 v[62:65], v[158:161], v[174:177], v[62:65]
	v_mfma_f32_16x16x32_bf16 v[58:61], v[166:169], v[174:177], v[58:61]
	v_mfma_f32_16x16x32_bf16 v[54:57], v[158:161], v[182:185], v[54:57]
	v_mfma_f32_16x16x32_bf16 v[46:49], v[166:169], v[182:185], v[46:49]
	v_mfma_f32_16x16x32_bf16 v[38:41], v[158:161], v[190:193], v[38:41]
	v_mfma_f32_16x16x32_bf16 v[30:33], v[166:169], v[190:193], v[30:33]
	v_mfma_f32_16x16x32_bf16 v[22:25], v[158:161], v[198:201], v[22:25]
	v_mfma_f32_16x16x32_bf16 v[14:17], v[166:169], v[198:201], v[14:17]
	v_mfma_f32_16x16x32_bf16 v[50:53], v[202:205], v[170:173], v[50:53]
	v_mfma_f32_16x16x32_bf16 v[42:45], v[210:213], v[170:173], v[42:45]
	v_mfma_f32_16x16x32_bf16 v[34:37], v[202:205], v[178:181], v[34:37]
	v_mfma_f32_16x16x32_bf16 v[26:29], v[210:213], v[178:181], v[26:29]
	v_mfma_f32_16x16x32_bf16 v[18:21], v[202:205], v[186:189], v[18:21]
	v_mfma_f32_16x16x32_bf16 v[10:13], v[210:213], v[186:189], v[10:13]
	v_mfma_f32_16x16x32_bf16 v[6:9], v[202:205], v[194:197], v[6:9]
	v_mfma_f32_16x16x32_bf16 v[2:5], v[210:213], v[194:197], v[2:5]
	v_mfma_f32_16x16x32_bf16 v[50:53], v[206:209], v[174:177], v[50:53]
	v_mfma_f32_16x16x32_bf16 v[42:45], v[214:217], v[174:177], v[42:45]
	v_mfma_f32_16x16x32_bf16 v[34:37], v[206:209], v[182:185], v[34:37]
	v_mfma_f32_16x16x32_bf16 v[26:29], v[214:217], v[182:185], v[26:29]
	v_mfma_f32_16x16x32_bf16 v[18:21], v[206:209], v[190:193], v[18:21]
	v_mfma_f32_16x16x32_bf16 v[10:13], v[214:217], v[190:193], v[10:13]
	v_mfma_f32_16x16x32_bf16 v[6:9], v[206:209], v[198:201], v[6:9]
	v_mfma_f32_16x16x32_bf16 v[2:5], v[214:217], v[198:201], v[2:5]
	s_setprio 0
	s_add_i32 s94, s94, 2
	s_add_u32 s19, s19, 0x100
	s_addc_u32 s93, s93, 0
	s_add_u32 s34, s34, 0x100
	s_addc_u32 s35, s35, 0
	s_cmp_gt_u32 s94, 61
	s_barrier
	s_cbranch_scc0 .LBB0_670
	s_waitcnt vmcnt(6)
	s_cmp_lt_i32 s92, 2
	s_cbranch_scc1 .LBB0_675
	s_cmp_eq_u32 s92, 2
	s_mov_b64 s[34:35], -1
	s_cbranch_scc0 .LBB0_674
	v_lshl_add_u32 v146, s26, 8, v1
	v_or_b32_e32 v156, 16, v146
	v_ashrrev_i32_e32 v147, 31, v146
	v_ashrrev_i32_e32 v157, 31, v156
	v_lshlrev_b64 v[154:155], 10, v[146:147]
	v_lshlrev_b64 v[156:157], 10, v[156:157]
	v_lshl_add_u64 v[154:155], v[138:139], 0, v[154:155]
	v_lshl_add_u64 v[156:157], v[138:139], 0, v[156:157]
	global_store_dwordx4 v[154:155], v[126:129], off
	global_store_dwordx4 v[154:155], v[122:125], off offset:16
	global_store_dwordx4 v[154:155], v[114:117], off offset:512
	global_store_dwordx4 v[154:155], v[106:109], off offset:528
	global_store_dwordx4 v[156:157], v[118:121], off
	global_store_dwordx4 v[156:157], v[110:113], off offset:16
	global_store_dwordx4 v[156:157], v[98:101], off offset:512
	global_store_dwordx4 v[156:157], v[90:93], off offset:528
	v_or_b32_e32 v156, 32, v146
	v_ashrrev_i32_e32 v157, 31, v156
	v_lshlrev_b64 v[156:157], 10, v[156:157]
	v_or_b32_e32 v146, 48, v146
	v_lshl_add_u64 v[156:157], v[138:139], 0, v[156:157]
	v_ashrrev_i32_e32 v147, 31, v146
	global_store_dwordx4 v[156:157], v[102:105], off
	global_store_dwordx4 v[156:157], v[94:97], off offset:16
	global_store_dwordx4 v[156:157], v[82:85], off offset:512
	global_store_dwordx4 v[156:157], v[74:77], off offset:528
	v_lshlrev_b64 v[146:147], 10, v[146:147]
	v_add_co_u32_e32 v156, vcc, s87, v154
	v_lshl_add_u64 v[146:147], v[138:139], 0, v[146:147]
	s_mov_b64 s[28:29], 0x20000
	v_addc_co_u32_e32 v157, vcc, 0, v155, vcc
	global_store_dwordx4 v[146:147], v[86:89], off
	global_store_dwordx4 v[146:147], v[78:81], off offset:16
	global_store_dwordx4 v[146:147], v[70:73], off offset:512
	global_store_dwordx4 v[146:147], v[66:69], off offset:528
	v_lshl_add_u64 v[146:147], v[154:155], 0, s[28:29]
	global_store_dwordx4 v[156:157], v[62:65], off
	global_store_dwordx4 v[146:147], v[58:61], off offset:16
	global_store_dwordx4 v[146:147], v[50:53], off offset:512
	global_store_dwordx4 v[146:147], v[42:45], off offset:528
	v_add_co_u32_e32 v156, vcc, s88, v154
	v_lshl_add_u64 v[146:147], v[154:155], 0, s[6:7]
	s_nop 0
	v_addc_co_u32_e32 v157, vcc, 0, v155, vcc
	global_store_dwordx4 v[156:157], v[54:57], off
	global_store_dwordx4 v[146:147], v[46:49], off offset:16
	global_store_dwordx4 v[146:147], v[34:37], off offset:512
	global_store_dwordx4 v[146:147], v[26:29], off offset:528
	v_add_co_u32_e32 v156, vcc, s89, v154
	v_lshl_add_u64 v[146:147], v[154:155], 0, s[12:13]
	s_nop 0
	v_addc_co_u32_e32 v157, vcc, 0, v155, vcc
	global_store_dwordx4 v[156:157], v[38:41], off
	global_store_dwordx4 v[146:147], v[30:33], off offset:16
	global_store_dwordx4 v[146:147], v[18:21], off offset:512
	global_store_dwordx4 v[146:147], v[10:13], off offset:528
	v_lshl_add_u64 v[146:147], v[154:155], 0, s[14:15]
	v_add_co_u32_e32 v154, vcc, 0x2c000, v154
	s_mov_b64 s[34:35], 0
	s_nop 0
	v_addc_co_u32_e32 v155, vcc, 0, v155, vcc
	global_store_dwordx4 v[154:155], v[22:25], off
	global_store_dwordx4 v[146:147], v[14:17], off offset:16
	global_store_dwordx4 v[146:147], v[6:9], off offset:512
	global_store_dwordx4 v[146:147], v[2:5], off offset:528

.LBB0_2485:
	ds_read_b128 v[152:155], v148
	ds_read_b128 v[156:159], v148 offset:1024
	ds_read_b128 v[160:163], v148 offset:2048
	ds_read_b128 v[164:167], v148 offset:3072
	ds_read_b128 v[200:203], v150
	ds_read_b128 v[204:207], v150 offset:1024
	ds_read_b128 v[208:211], v150 offset:2048
	ds_read_b128 v[212:215], v150 offset:3072
	s_add_u32 s28, s50, 0xfff00080
	s_addc_u32 s29, s51, -1
	s_cmp_eq_u32 s81, 60
	s_cselect_b32 s55, s45, s29
	s_cselect_b32 s54, s44, s28
	s_cselect_b32 s53, s47, s41
	s_cselect_b32 s52, s46, s39
	v_lshl_add_u64 v[144:145], s[50:51], 0, v[140:141]
	s_add_i32 m0, s49, 0xc000
	ds_read_b128 v[168:171], v149
	ds_read_b128 v[172:175], v149 offset:1024
	ds_read_b128 v[176:179], v149 offset:2048
	ds_read_b128 v[180:183], v149 offset:3072
	ds_read_b128 v[184:187], v149 offset:4096
	ds_read_b128 v[188:191], v149 offset:5120
	ds_read_b128 v[192:195], v149 offset:6144
	ds_read_b128 v[196:199], v149 offset:7168
	global_load_lds_dwordx4 v[144:145], off
	v_lshl_add_u64 v[144:145], s[50:51], 0, v[138:139]
	s_add_i32 m0, s49, 0xe000
	s_nop 0
	global_load_lds_dwordx4 v[144:145], off
	s_cmp_eq_u32 s81, -2
	s_cbranch_scc1 .Lk2_skip_2485
	s_waitcnt vmcnt(8)
.Lk2_skip_2485:
	s_waitcnt lgkmcnt(0)
	s_barrier
	s_setprio 1
	v_mfma_f32_16x16x32_bf16 v[126:129], v[152:155], v[168:171], v[126:129]
	v_mfma_f32_16x16x32_bf16 v[122:125], v[160:163], v[168:171], v[122:125]
	v_mfma_f32_16x16x32_bf16 v[114:117], v[152:155], v[176:179], v[114:117]
	v_mfma_f32_16x16x32_bf16 v[106:109], v[160:163], v[176:179], v[106:109]
	v_mfma_f32_16x16x32_bf16 v[98:101], v[152:155], v[184:187], v[98:101]
	v_mfma_f32_16x16x32_bf16 v[90:93], v[160:163], v[184:187], v[90:93]
	v_mfma_f32_16x16x32_bf16 v[82:85], v[152:155], v[192:195], v[82:85]
	v_mfma_f32_16x16x32_bf16 v[74:77], v[160:163], v[192:195], v[74:77]
	v_mfma_f32_16x16x32_bf16 v[126:129], v[156:159], v[172:175], v[126:129]
	v_mfma_f32_16x16x32_bf16 v[122:125], v[164:167], v[172:175], v[122:125]
	v_mfma_f32_16x16x32_bf16 v[114:117], v[156:159], v[180:183], v[114:117]
	v_mfma_f32_16x16x32_bf16 v[106:109], v[164:167], v[180:183], v[106:109]
	v_mfma_f32_16x16x32_bf16 v[98:101], v[156:159], v[188:191], v[98:101]
	v_mfma_f32_16x16x32_bf16 v[90:93], v[164:167], v[188:191], v[90:93]
	v_mfma_f32_16x16x32_bf16 v[82:85], v[156:159], v[196:199], v[82:85]
	v_mfma_f32_16x16x32_bf16 v[74:77], v[164:167], v[196:199], v[74:77]
	v_mfma_f32_16x16x32_bf16 v[118:121], v[200:203], v[168:171], v[118:121]
	v_mfma_f32_16x16x32_bf16 v[110:113], v[208:211], v[168:171], v[110:113]
	v_mfma_f32_16x16x32_bf16 v[102:105], v[200:203], v[176:179], v[102:105]
	v_mfma_f32_16x16x32_bf16 v[94:97], v[208:211], v[176:179], v[94:97]
	v_mfma_f32_16x16x32_bf16 v[86:89], v[200:203], v[184:187], v[86:89]
	v_mfma_f32_16x16x32_bf16 v[78:81], v[208:211], v[184:187], v[78:81]
	v_mfma_f32_16x16x32_bf16 v[70:73], v[200:203], v[192:195], v[70:73]
	v_mfma_f32_16x16x32_bf16 v[66:69], v[208:211], v[192:195], v[66:69]
	v_mfma_f32_16x16x32_bf16 v[118:121], v[204:207], v[172:175], v[118:121]
	v_mfma_f32_16x16x32_bf16 v[110:113], v[212:215], v[172:175], v[110:113]
	v_mfma_f32_16x16x32_bf16 v[102:105], v[204:207], v[180:183], v[102:105]
	v_mfma_f32_16x16x32_bf16 v[94:97], v[212:215], v[180:183], v[94:97]
	v_mfma_f32_16x16x32_bf16 v[86:89], v[204:207], v[188:191], v[86:89]
	v_mfma_f32_16x16x32_bf16 v[78:81], v[212:215], v[188:191], v[78:81]
	v_mfma_f32_16x16x32_bf16 v[70:73], v[204:207], v[196:199], v[70:73]
	v_mfma_f32_16x16x32_bf16 v[66:69], v[212:215], v[196:199], v[66:69]
	s_setprio 0
	s_barrier
	ds_read_b128 v[168:171], v149 offset:16384
	ds_read_b128 v[172:175], v149 offset:17408
	ds_read_b128 v[176:179], v149 offset:18432
	ds_read_b128 v[180:183], v149 offset:19456
	ds_read_b128 v[184:187], v149 offset:20480
	ds_read_b128 v[188:191], v149 offset:21504
	ds_read_b128 v[192:195], v149 offset:22528
	ds_read_b128 v[196:199], v149 offset:23552
	s_add_i32 s28, s74, s67
	v_lshl_add_u64 v[144:145], s[52:53], 0, v[134:135]
	s_mov_b32 m0, s28
	s_nop 0
	global_load_lds_dwordx4 v[144:145], off
	v_lshl_add_u64 v[216:217], s[52:53], 0, v[130:131]
	s_add_i32 m0, s28, 0x2000
	s_nop 0
	global_load_lds_dwordx4 v[216:217], off
	s_mov_b32 m0, s49
	v_lshl_add_u64 v[218:219], s[54:55], 0, v[136:137]
	global_load_lds_dwordx4 v[218:219], off
	v_lshl_add_u64 v[220:221], s[54:55], 0, v[132:133]
	s_mov_b32 m0, s68
	s_nop 0
	global_load_lds_dwordx4 v[220:221], off
	s_add_u32 s28, s52, 0x100000
	s_addc_u32 s29, s53, 0
	s_add_i32 s82, s75, s67
	v_lshl_add_u64 v[226:227], s[28:29], 0, v[134:135]
	s_mov_b32 m0, s82
	s_nop 0
	global_load_lds_dwordx4 v[226:227], off
	v_lshl_add_u64 v[226:227], s[28:29], 0, v[130:131]
	s_add_i32 m0, s82, 0x2000
	s_nop 0
	global_load_lds_dwordx4 v[226:227], off
	s_waitcnt vmcnt(8)
	s_waitcnt lgkmcnt(0)
	s_barrier
	s_setprio 1
	v_mfma_f32_16x16x32_bf16 v[62:65], v[152:155], v[168:171], v[62:65]
	v_mfma_f32_16x16x32_bf16 v[58:61], v[160:163], v[168:171], v[58:61]
	v_mfma_f32_16x16x32_bf16 v[54:57], v[152:155], v[176:179], v[54:57]
	v_mfma_f32_16x16x32_bf16 v[46:49], v[160:163], v[176:179], v[46:49]
	v_mfma_f32_16x16x32_bf16 v[38:41], v[152:155], v[184:187], v[38:41]
	v_mfma_f32_16x16x32_bf16 v[30:33], v[160:163], v[184:187], v[30:33]
	v_mfma_f32_16x16x32_bf16 v[22:25], v[152:155], v[192:195], v[22:25]
	v_mfma_f32_16x16x32_bf16 v[14:17], v[160:163], v[192:195], v[14:17]
	v_mfma_f32_16x16x32_bf16 v[62:65], v[156:159], v[172:175], v[62:65]
	v_mfma_f32_16x16x32_bf16 v[58:61], v[164:167], v[172:175], v[58:61]
	v_mfma_f32_16x16x32_bf16 v[54:57], v[156:159], v[180:183], v[54:57]
	v_mfma_f32_16x16x32_bf16 v[46:49], v[164:167], v[180:183], v[46:49]
	v_mfma_f32_16x16x32_bf16 v[38:41], v[156:159], v[188:191], v[38:41]
	v_mfma_f32_16x16x32_bf16 v[30:33], v[164:167], v[188:191], v[30:33]
	v_mfma_f32_16x16x32_bf16 v[22:25], v[156:159], v[196:199], v[22:25]
	v_mfma_f32_16x16x32_bf16 v[14:17], v[164:167], v[196:199], v[14:17]
	v_mfma_f32_16x16x32_bf16 v[50:53], v[200:203], v[168:171], v[50:53]
	v_mfma_f32_16x16x32_bf16 v[42:45], v[208:211], v[168:171], v[42:45]
	v_mfma_f32_16x16x32_bf16 v[34:37], v[200:203], v[176:179], v[34:37]
	v_mfma_f32_16x16x32_bf16 v[26:29], v[208:211], v[176:179], v[26:29]
	v_mfma_f32_16x16x32_bf16 v[18:21], v[200:203], v[184:187], v[18:21]
	v_mfma_f32_16x16x32_bf16 v[10:13], v[208:211], v[184:187], v[10:13]
	v_mfma_f32_16x16x32_bf16 v[6:9], v[200:203], v[192:195], v[6:9]
	v_mfma_f32_16x16x32_bf16 v[2:5], v[208:211], v[192:195], v[2:5]
	v_mfma_f32_16x16x32_bf16 v[50:53], v[204:207], v[172:175], v[50:53]
	v_mfma_f32_16x16x32_bf16 v[42:45], v[212:215], v[172:175], v[42:45]
	v_mfma_f32_16x16x32_bf16 v[34:37], v[204:207], v[180:183], v[34:37]
	v_mfma_f32_16x16x32_bf16 v[26:29], v[212:215], v[180:183], v[26:29]
	v_mfma_f32_16x16x32_bf16 v[18:21], v[204:207], v[188:191], v[18:21]
	v_mfma_f32_16x16x32_bf16 v[10:13], v[212:215], v[188:191], v[10:13]
	v_mfma_f32_16x16x32_bf16 v[6:9], v[204:207], v[196:199], v[6:9]
	v_mfma_f32_16x16x32_bf16 v[2:5], v[212:215], v[196:199], v[2:5]
	s_setprio 0
	s_add_i32 s82, 0, 0x18000
	v_add_u32_e32 v151, s82, v146
	s_barrier
	ds_read_b128 v[152:155], v151
	ds_read_b128 v[156:159], v151 offset:1024
	ds_read_b128 v[160:163], v151 offset:2048
	ds_read_b128 v[164:167], v151 offset:3072
	ds_read_b128 v[200:203], v151 offset:16384
	ds_read_b128 v[204:207], v151 offset:17408
	ds_read_b128 v[208:211], v151 offset:18432
	ds_read_b128 v[212:215], v151 offset:19456
	s_add_u32 s28, s54, 0x100000
	s_addc_u32 s29, s55, 0
	s_mov_b32 m0, s69
	v_lshl_add_u64 v[226:227], s[28:29], 0, v[136:137]
	ds_read_b128 v[168:171], v149 offset:32768
	ds_read_b128 v[172:175], v149 offset:33792
	ds_read_b128 v[176:179], v149 offset:34816
	ds_read_b128 v[180:183], v149 offset:35840
	ds_read_b128 v[184:187], v149 offset:36864
	ds_read_b128 v[188:191], v149 offset:37888
	ds_read_b128 v[192:195], v149 offset:38912
	ds_read_b128 v[196:199], v149 offset:39936
	global_load_lds_dwordx4 v[226:227], off
	v_lshl_add_u64 v[226:227], s[28:29], 0, v[132:133]
	s_mov_b32 m0, s70
	s_nop 0
	global_load_lds_dwordx4 v[226:227], off
	s_waitcnt vmcnt(8)
	s_waitcnt lgkmcnt(0)
	s_barrier
	s_setprio 1
	v_mfma_f32_16x16x32_bf16 v[126:129], v[152:155], v[168:171], v[126:129]
	v_mfma_f32_16x16x32_bf16 v[122:125], v[160:163], v[168:171], v[122:125]
	v_mfma_f32_16x16x32_bf16 v[114:117], v[152:155], v[176:179], v[114:117]
	v_mfma_f32_16x16x32_bf16 v[106:109], v[160:163], v[176:179], v[106:109]
	v_mfma_f32_16x16x32_bf16 v[98:101], v[152:155], v[184:187], v[98:101]
	v_mfma_f32_16x16x32_bf16 v[90:93], v[160:163], v[184:187], v[90:93]
	v_mfma_f32_16x16x32_bf16 v[82:85], v[152:155], v[192:195], v[82:85]
	v_mfma_f32_16x16x32_bf16 v[74:77], v[160:163], v[192:195], v[74:77]
	v_mfma_f32_16x16x32_bf16 v[126:129], v[156:159], v[172:175], v[126:129]
	v_mfma_f32_16x16x32_bf16 v[122:125], v[164:167], v[172:175], v[122:125]
	v_mfma_f32_16x16x32_bf16 v[114:117], v[156:159], v[180:183], v[114:117]
	v_mfma_f32_16x16x32_bf16 v[106:109], v[164:167], v[180:183], v[106:109]
	v_mfma_f32_16x16x32_bf16 v[98:101], v[156:159], v[188:191], v[98:101]
	v_mfma_f32_16x16x32_bf16 v[90:93], v[164:167], v[188:191], v[90:93]
	v_mfma_f32_16x16x32_bf16 v[82:85], v[156:159], v[196:199], v[82:85]
	v_mfma_f32_16x16x32_bf16 v[74:77], v[164:167], v[196:199], v[74:77]
	v_mfma_f32_16x16x32_bf16 v[118:121], v[200:203], v[168:171], v[118:121]
	v_mfma_f32_16x16x32_bf16 v[110:113], v[208:211], v[168:171], v[110:113]
	v_mfma_f32_16x16x32_bf16 v[102:105], v[200:203], v[176:179], v[102:105]
	v_mfma_f32_16x16x32_bf16 v[94:97], v[208:211], v[176:179], v[94:97]
	v_mfma_f32_16x16x32_bf16 v[86:89], v[200:203], v[184:187], v[86:89]
	v_mfma_f32_16x16x32_bf16 v[78:81], v[208:211], v[184:187], v[78:81]
	v_mfma_f32_16x16x32_bf16 v[70:73], v[200:203], v[192:195], v[70:73]
	v_mfma_f32_16x16x32_bf16 v[66:69], v[208:211], v[192:195], v[66:69]
	v_mfma_f32_16x16x32_bf16 v[118:121], v[204:207], v[172:175], v[118:121]
	v_mfma_f32_16x16x32_bf16 v[110:113], v[212:215], v[172:175], v[110:113]
	v_mfma_f32_16x16x32_bf16 v[102:105], v[204:207], v[180:183], v[102:105]
	v_mfma_f32_16x16x32_bf16 v[94:97], v[212:215], v[180:183], v[94:97]
	v_mfma_f32_16x16x32_bf16 v[86:89], v[204:207], v[188:191], v[86:89]
	v_mfma_f32_16x16x32_bf16 v[78:81], v[212:215], v[188:191], v[78:81]
	v_mfma_f32_16x16x32_bf16 v[70:73], v[204:207], v[196:199], v[70:73]
	v_mfma_f32_16x16x32_bf16 v[66:69], v[212:215], v[196:199], v[66:69]
	s_setprio 0
	s_barrier
	ds_read_b128 v[168:171], v149 offset:49152
	ds_read_b128 v[172:175], v149 offset:50176
	ds_read_b128 v[176:179], v149 offset:51200
	ds_read_b128 v[180:183], v149 offset:52224
	ds_read_b128 v[184:187], v149 offset:53248
	ds_read_b128 v[188:191], v149 offset:54272
	ds_read_b128 v[192:195], v149 offset:55296
	ds_read_b128 v[196:199], v149 offset:56320
	s_add_i32 s54, 0, 0x1c000
	s_add_i32 s28, s82, s67
	v_lshl_add_u64 v[144:145], v[144:145], 0, s[22:23]
	s_mov_b32 m0, s28
	s_nop 0
	global_load_lds_dwordx4 v[144:145], off
	v_lshl_add_u64 v[144:145], v[216:217], 0, s[22:23]
	s_add_i32 m0, s28, 0x2000
	s_nop 0
	global_load_lds_dwordx4 v[144:145], off
	s_mov_b32 m0, s72
	v_lshl_add_u64 v[144:145], v[218:219], 0, s[22:23]
	global_load_lds_dwordx4 v[144:145], off
	v_lshl_add_u64 v[144:145], v[220:221], 0, s[22:23]
	s_mov_b32 m0, s73
	s_nop 0
	global_load_lds_dwordx4 v[144:145], off
	s_add_u32 s28, s52, 0x100080
	s_addc_u32 s29, s53, 0
	s_add_i32 s52, s54, s67
	v_lshl_add_u64 v[144:145], s[28:29], 0, v[134:135]
	s_mov_b32 m0, s52
	s_nop 0
	global_load_lds_dwordx4 v[144:145], off
	v_lshl_add_u64 v[144:145], s[28:29], 0, v[130:131]
	s_add_i32 m0, s52, 0x2000
	s_nop 0
	global_load_lds_dwordx4 v[144:145], off
	s_waitcnt vmcnt(8)
	s_waitcnt lgkmcnt(0)
	s_barrier
	s_setprio 1
	v_mfma_f32_16x16x32_bf16 v[62:65], v[152:155], v[168:171], v[62:65]
	v_mfma_f32_16x16x32_bf16 v[58:61], v[160:163], v[168:171], v[58:61]
	v_mfma_f32_16x16x32_bf16 v[54:57], v[152:155], v[176:179], v[54:57]
	v_mfma_f32_16x16x32_bf16 v[46:49], v[160:163], v[176:179], v[46:49]
	v_mfma_f32_16x16x32_bf16 v[38:41], v[152:155], v[184:187], v[38:41]
	v_mfma_f32_16x16x32_bf16 v[30:33], v[160:163], v[184:187], v[30:33]
	v_mfma_f32_16x16x32_bf16 v[22:25], v[152:155], v[192:195], v[22:25]
	v_mfma_f32_16x16x32_bf16 v[14:17], v[160:163], v[192:195], v[14:17]
	v_mfma_f32_16x16x32_bf16 v[62:65], v[156:159], v[172:175], v[62:65]
	v_mfma_f32_16x16x32_bf16 v[58:61], v[164:167], v[172:175], v[58:61]
	v_mfma_f32_16x16x32_bf16 v[54:57], v[156:159], v[180:183], v[54:57]
	v_mfma_f32_16x16x32_bf16 v[46:49], v[164:167], v[180:183], v[46:49]
	v_mfma_f32_16x16x32_bf16 v[38:41], v[156:159], v[188:191], v[38:41]
	v_mfma_f32_16x16x32_bf16 v[30:33], v[164:167], v[188:191], v[30:33]
	v_mfma_f32_16x16x32_bf16 v[22:25], v[156:159], v[196:199], v[22:25]
	v_mfma_f32_16x16x32_bf16 v[14:17], v[164:167], v[196:199], v[14:17]
	v_mfma_f32_16x16x32_bf16 v[50:53], v[200:203], v[168:171], v[50:53]
	v_mfma_f32_16x16x32_bf16 v[42:45], v[208:211], v[168:171], v[42:45]
	v_mfma_f32_16x16x32_bf16 v[34:37], v[200:203], v[176:179], v[34:37]
	v_mfma_f32_16x16x32_bf16 v[26:29], v[208:211], v[176:179], v[26:29]
	v_mfma_f32_16x16x32_bf16 v[18:21], v[200:203], v[184:187], v[18:21]
	v_mfma_f32_16x16x32_bf16 v[10:13], v[208:211], v[184:187], v[10:13]
	v_mfma_f32_16x16x32_bf16 v[6:9], v[200:203], v[192:195], v[6:9]
	v_mfma_f32_16x16x32_bf16 v[2:5], v[208:211], v[192:195], v[2:5]
	v_mfma_f32_16x16x32_bf16 v[50:53], v[204:207], v[172:175], v[50:53]
	v_mfma_f32_16x16x32_bf16 v[42:45], v[212:215], v[172:175], v[42:45]
	v_mfma_f32_16x16x32_bf16 v[34:37], v[204:207], v[180:183], v[34:37]
	v_mfma_f32_16x16x32_bf16 v[26:29], v[212:215], v[180:183], v[26:29]
	v_mfma_f32_16x16x32_bf16 v[18:21], v[204:207], v[188:191], v[18:21]
	v_mfma_f32_16x16x32_bf16 v[10:13], v[212:215], v[188:191], v[10:13]
	v_mfma_f32_16x16x32_bf16 v[6:9], v[204:207], v[196:199], v[6:9]
	v_mfma_f32_16x16x32_bf16 v[2:5], v[212:215], v[196:199], v[2:5]
	s_setprio 0
	s_add_i32 s81, s81, 2
	s_add_u32 s39, s39, 0x100
	s_addc_u32 s41, s41, 0
	s_add_u32 s50, s50, 0x100
	s_addc_u32 s51, s51, 0
	s_cmp_gt_u32 s81, 61
	s_barrier
	s_cbranch_scc0 .LBB0_2485
	s_waitcnt vmcnt(6)
	v_lshl_add_u32 v152, s48, 8, v1
	v_lshl_or_b32 v144, s80, 8, v147
	v_ashrrev_i32_e32 v153, 31, v152
	v_ashrrev_i32_e32 v145, 31, v144
	v_lshlrev_b64 v[154:155], 13, v[152:153]
	v_lshl_add_u64 v[154:155], s[18:19], 0, v[154:155]
	v_lshlrev_b64 v[156:157], 1, v[144:145]
	v_lshl_add_u64 v[144:145], v[154:155], 0, v[156:157]
	v_cvt_pk_bf16_f32 v126, v126, v127
	v_cvt_pk_bf16_f32 v127, v128, v129
	v_cvt_pk_bf16_f32 v128, v122, v123
	v_cvt_pk_bf16_f32 v129, v124, v125
	global_store_dwordx4 v[144:145], v[126:129], off
	v_cvt_pk_bf16_f32 v118, v118, v119
	v_cvt_pk_bf16_f32 v119, v120, v121
	v_cvt_pk_bf16_f32 v120, v110, v111
	v_or_b32_e32 v110, 16, v152
	v_ashrrev_i32_e32 v111, 31, v110
	v_lshlrev_b64 v[110:111], 13, v[110:111]
	v_lshl_add_u64 v[110:111], s[18:19], 0, v[110:111]
	v_cvt_pk_bf16_f32 v121, v112, v113
	global_store_dwordx4 v[144:145], v[118:121], off offset:256
	s_mov_b32 s48, s40
	s_mov_b32 s80, s38
	v_lshl_add_u64 v[118:119], v[110:111], 0, v[156:157]
	v_cvt_pk_bf16_f32 v110, v114, v115
	v_cvt_pk_bf16_f32 v111, v116, v117
	v_cvt_pk_bf16_f32 v112, v106, v107
	v_cvt_pk_bf16_f32 v113, v108, v109
	global_store_dwordx4 v[118:119], v[110:113], off
	v_cvt_pk_bf16_f32 v102, v102, v103
	v_cvt_pk_bf16_f32 v103, v104, v105
	v_cvt_pk_bf16_f32 v104, v94, v95
	v_or_b32_e32 v94, 32, v152
	v_ashrrev_i32_e32 v95, 31, v94
	v_lshlrev_b64 v[94:95], 13, v[94:95]
	v_lshl_add_u64 v[94:95], s[18:19], 0, v[94:95]
	v_cvt_pk_bf16_f32 v105, v96, v97
	global_store_dwordx4 v[118:119], v[102:105], off offset:256
	s_mov_b64 s[52:53], s[46:47]
	s_mov_b64 s[50:51], s[44:45]
	v_lshl_add_u64 v[102:103], v[94:95], 0, v[156:157]
	v_cvt_pk_bf16_f32 v94, v98, v99
	v_cvt_pk_bf16_f32 v95, v100, v101
	v_cvt_pk_bf16_f32 v96, v90, v91
	v_cvt_pk_bf16_f32 v97, v92, v93
	global_store_dwordx4 v[102:103], v[94:97], off
	v_cvt_pk_bf16_f32 v86, v86, v87
	v_cvt_pk_bf16_f32 v87, v88, v89
	v_cvt_pk_bf16_f32 v88, v78, v79
	v_or_b32_e32 v78, 48, v152
	v_ashrrev_i32_e32 v79, 31, v78
	v_lshlrev_b64 v[78:79], 13, v[78:79]
	v_lshl_add_u64 v[78:79], s[18:19], 0, v[78:79]
	v_cvt_pk_bf16_f32 v89, v80, v81
	global_store_dwordx4 v[102:103], v[86:89], off offset:256
	s_nop 1
	v_lshl_add_u64 v[86:87], v[78:79], 0, v[156:157]
	v_cvt_pk_bf16_f32 v78, v82, v83
	v_cvt_pk_bf16_f32 v79, v84, v85
	v_cvt_pk_bf16_f32 v80, v74, v75
	v_cvt_pk_bf16_f32 v81, v76, v77
	global_store_dwordx4 v[86:87], v[78:81], off
	v_cvt_pk_bf16_f32 v70, v70, v71
	v_cvt_pk_bf16_f32 v71, v72, v73
	v_cvt_pk_bf16_f32 v72, v66, v67
	v_cvt_pk_bf16_f32 v73, v68, v69
	global_store_dwordx4 v[86:87], v[70:73], off offset:256
	v_cvt_pk_bf16_f32 v62, v62, v63
	v_cvt_pk_bf16_f32 v63, v64, v65
	v_cvt_pk_bf16_f32 v64, v58, v59
	v_add_co_u32_e32 v58, vcc, s76, v144
	v_lshl_add_u64 v[66:67], v[144:145], 0, s[20:21]
	s_nop 0
	v_addc_co_u32_e32 v59, vcc, 0, v145, vcc
	v_cvt_pk_bf16_f32 v65, v60, v61
	global_store_dwordx4 v[58:59], v[62:65], off
	v_cvt_pk_bf16_f32 v50, v50, v51
	v_cvt_pk_bf16_f32 v51, v52, v53
	v_cvt_pk_bf16_f32 v52, v42, v43
	v_cvt_pk_bf16_f32 v53, v44, v45
	global_store_dwordx4 v[66:67], v[50:53], off offset:256
	v_cvt_pk_bf16_f32 v42, v54, v55
	v_cvt_pk_bf16_f32 v43, v56, v57
	v_cvt_pk_bf16_f32 v44, v46, v47
	v_add_co_u32_e32 v46, vcc, s77, v144
	s_nop 0
	v_lshl_add_u64 v[50:51], v[144:145], 0, s[26:27]
	v_addc_co_u32_e32 v47, vcc, 0, v145, vcc
	v_cvt_pk_bf16_f32 v45, v48, v49
	global_store_dwordx4 v[46:47], v[42:45], off
	v_cvt_pk_bf16_f32 v34, v34, v35
	v_cvt_pk_bf16_f32 v35, v36, v37
	v_cvt_pk_bf16_f32 v36, v26, v27
	v_cvt_pk_bf16_f32 v37, v28, v29
	global_store_dwordx4 v[50:51], v[34:37], off offset:256
	v_cvt_pk_bf16_f32 v26, v38, v39
	v_cvt_pk_bf16_f32 v27, v40, v41
	v_cvt_pk_bf16_f32 v28, v30, v31
	v_add_co_u32_e32 v30, vcc, s78, v144
	s_nop 0
	v_lshl_add_u64 v[34:35], v[144:145], 0, s[34:35]
	v_addc_co_u32_e32 v31, vcc, 0, v145, vcc
	v_cvt_pk_bf16_f32 v29, v32, v33
	global_store_dwordx4 v[30:31], v[26:29], off
	v_cvt_pk_bf16_f32 v18, v18, v19
	v_cvt_pk_bf16_f32 v19, v20, v21
	v_cvt_pk_bf16_f32 v20, v10, v11
	v_cvt_pk_bf16_f32 v21, v12, v13
	global_store_dwordx4 v[34:35], v[18:21], off offset:256
	v_cvt_pk_bf16_f32 v10, v22, v23
	v_cvt_pk_bf16_f32 v11, v24, v25
	v_cvt_pk_bf16_f32 v12, v14, v15
	v_add_co_u32_e32 v14, vcc, s79, v144
	s_nop 0
	v_lshl_add_u64 v[18:19], v[144:145], 0, s[36:37]
	v_addc_co_u32_e32 v15, vcc, 0, v145, vcc
	s_and_b64 vcc, exec, s[6:7]
	v_cvt_pk_bf16_f32 v13, v16, v17
	global_store_dwordx4 v[14:15], v[10:13], off
	v_cvt_pk_bf16_f32 v6, v6, v7
	v_cvt_pk_bf16_f32 v7, v8, v9
	v_cvt_pk_bf16_f32 v8, v2, v3
	v_cvt_pk_bf16_f32 v9, v4, v5
	global_store_dwordx4 v[18:19], v[6:9], off offset:256
	s_cbranch_vccz .LBB0_2478
	s_waitcnt vmcnt(0)
	s_cmpk_gt_u32 s66, 0xff
	s_cbranch_scc1 .LBB0_2489
	s_barrier

.LBB0_3048:
	ds_read_b128 v[154:157], v150
	ds_read_b128 v[158:161], v150 offset:1024
	ds_read_b128 v[162:165], v150 offset:2048
	ds_read_b128 v[166:169], v150 offset:3072
	ds_read_b128 v[202:205], v152
	ds_read_b128 v[206:209], v152 offset:1024
	ds_read_b128 v[210:213], v152 offset:2048
	ds_read_b128 v[214:217], v152 offset:3072
	s_add_u32 s28, s38, 0xfff00080
	s_addc_u32 s29, s39, -1
	s_cmp_eq_u32 s72, 60
	s_cselect_b32 s45, s37, s29
	s_cselect_b32 s44, s36, s28
	s_cselect_b32 s41, s35, s71
	s_cselect_b32 s40, s34, s21
	v_lshl_add_u64 v[146:147], s[38:39], 0, v[142:143]
	s_add_i32 m0, s23, 0xc000
	ds_read_b128 v[170:173], v151
	ds_read_b128 v[174:177], v151 offset:1024
	ds_read_b128 v[178:181], v151 offset:2048
	ds_read_b128 v[182:185], v151 offset:3072
	ds_read_b128 v[186:189], v151 offset:4096
	ds_read_b128 v[190:193], v151 offset:5120
	ds_read_b128 v[194:197], v151 offset:6144
	ds_read_b128 v[198:201], v151 offset:7168
	global_load_lds_dwordx4 v[146:147], off
	v_lshl_add_u64 v[146:147], s[38:39], 0, v[140:141]
	s_add_i32 m0, s23, 0xe000
	s_nop 0
	global_load_lds_dwordx4 v[146:147], off
	s_cmp_eq_u32 s72, -2
	s_cbranch_scc1 .Lk2_skip_3048
	s_waitcnt vmcnt(8)
.Lk2_skip_3048:
	s_waitcnt lgkmcnt(0)
	s_barrier
	s_setprio 1
	v_mfma_f32_16x16x32_bf16 v[126:129], v[154:157], v[170:173], v[126:129]
	v_mfma_f32_16x16x32_bf16 v[122:125], v[162:165], v[170:173], v[122:125]
	v_mfma_f32_16x16x32_bf16 v[118:121], v[154:157], v[178:181], v[118:121]
	v_mfma_f32_16x16x32_bf16 v[110:113], v[162:165], v[178:181], v[110:113]
	v_mfma_f32_16x16x32_bf16 v[102:105], v[154:157], v[186:189], v[102:105]
	v_mfma_f32_16x16x32_bf16 v[94:97], v[162:165], v[186:189], v[94:97]
	v_mfma_f32_16x16x32_bf16 v[86:89], v[154:157], v[194:197], v[86:89]
	v_mfma_f32_16x16x32_bf16 v[78:81], v[162:165], v[194:197], v[78:81]
	v_mfma_f32_16x16x32_bf16 v[126:129], v[158:161], v[174:177], v[126:129]
	v_mfma_f32_16x16x32_bf16 v[122:125], v[166:169], v[174:177], v[122:125]
	v_mfma_f32_16x16x32_bf16 v[118:121], v[158:161], v[182:185], v[118:121]
	v_mfma_f32_16x16x32_bf16 v[110:113], v[166:169], v[182:185], v[110:113]
	v_mfma_f32_16x16x32_bf16 v[102:105], v[158:161], v[190:193], v[102:105]
	v_mfma_f32_16x16x32_bf16 v[94:97], v[166:169], v[190:193], v[94:97]
	v_mfma_f32_16x16x32_bf16 v[86:89], v[158:161], v[198:201], v[86:89]
	v_mfma_f32_16x16x32_bf16 v[78:81], v[166:169], v[198:201], v[78:81]
	v_mfma_f32_16x16x32_bf16 v[114:117], v[202:205], v[170:173], v[114:117]
	v_mfma_f32_16x16x32_bf16 v[106:109], v[210:213], v[170:173], v[106:109]
	v_mfma_f32_16x16x32_bf16 v[98:101], v[202:205], v[178:181], v[98:101]
	v_mfma_f32_16x16x32_bf16 v[90:93], v[210:213], v[178:181], v[90:93]
	v_mfma_f32_16x16x32_bf16 v[82:85], v[202:205], v[186:189], v[82:85]
	v_mfma_f32_16x16x32_bf16 v[74:77], v[210:213], v[186:189], v[74:77]
	v_mfma_f32_16x16x32_bf16 v[70:73], v[202:205], v[194:197], v[70:73]
	v_mfma_f32_16x16x32_bf16 v[66:69], v[210:213], v[194:197], v[66:69]
	v_mfma_f32_16x16x32_bf16 v[114:117], v[206:209], v[174:177], v[114:117]
	v_mfma_f32_16x16x32_bf16 v[106:109], v[214:217], v[174:177], v[106:109]
	v_mfma_f32_16x16x32_bf16 v[98:101], v[206:209], v[182:185], v[98:101]
	v_mfma_f32_16x16x32_bf16 v[90:93], v[214:217], v[182:185], v[90:93]
	v_mfma_f32_16x16x32_bf16 v[82:85], v[206:209], v[190:193], v[82:85]
	v_mfma_f32_16x16x32_bf16 v[74:77], v[214:217], v[190:193], v[74:77]
	v_mfma_f32_16x16x32_bf16 v[70:73], v[206:209], v[198:201], v[70:73]
	v_mfma_f32_16x16x32_bf16 v[66:69], v[214:217], v[198:201], v[66:69]
	s_setprio 0
	s_barrier
	ds_read_b128 v[170:173], v151 offset:16384
	ds_read_b128 v[174:177], v151 offset:17408
	ds_read_b128 v[178:181], v151 offset:18432
	ds_read_b128 v[182:185], v151 offset:19456
	ds_read_b128 v[186:189], v151 offset:20480
	ds_read_b128 v[190:193], v151 offset:21504
	ds_read_b128 v[194:197], v151 offset:22528
	ds_read_b128 v[198:201], v151 offset:23552
	s_add_i32 s28, s64, s54
	v_lshl_add_u64 v[146:147], s[40:41], 0, v[134:135]
	s_mov_b32 m0, s28
	s_nop 0
	global_load_lds_dwordx4 v[146:147], off
	v_lshl_add_u64 v[218:219], s[40:41], 0, v[130:131]
	s_add_i32 m0, s28, 0x2000
	s_nop 0
	global_load_lds_dwordx4 v[218:219], off
	s_mov_b32 m0, s23
	v_lshl_add_u64 v[220:221], s[44:45], 0, v[136:137]
	global_load_lds_dwordx4 v[220:221], off
	v_lshl_add_u64 v[222:223], s[44:45], 0, v[132:133]
	s_mov_b32 m0, s27
	s_nop 0
	global_load_lds_dwordx4 v[222:223], off
	s_add_u32 s28, s40, 0x100000
	s_addc_u32 s29, s41, 0
	s_add_i32 s73, s65, s54
	v_lshl_add_u64 v[226:227], s[28:29], 0, v[134:135]
	s_mov_b32 m0, s73
	s_nop 0
	global_load_lds_dwordx4 v[226:227], off
	v_lshl_add_u64 v[226:227], s[28:29], 0, v[130:131]
	s_add_i32 m0, s73, 0x2000
	s_nop 0
	global_load_lds_dwordx4 v[226:227], off
	s_waitcnt vmcnt(8)
	s_waitcnt lgkmcnt(0)
	s_barrier
	s_setprio 1
	v_mfma_f32_16x16x32_bf16 v[62:65], v[154:157], v[170:173], v[62:65]
	v_mfma_f32_16x16x32_bf16 v[58:61], v[162:165], v[170:173], v[58:61]
	v_mfma_f32_16x16x32_bf16 v[54:57], v[154:157], v[178:181], v[54:57]
	v_mfma_f32_16x16x32_bf16 v[46:49], v[162:165], v[178:181], v[46:49]
	v_mfma_f32_16x16x32_bf16 v[38:41], v[154:157], v[186:189], v[38:41]
	v_mfma_f32_16x16x32_bf16 v[30:33], v[162:165], v[186:189], v[30:33]
	v_mfma_f32_16x16x32_bf16 v[22:25], v[154:157], v[194:197], v[22:25]
	v_mfma_f32_16x16x32_bf16 v[14:17], v[162:165], v[194:197], v[14:17]
	v_mfma_f32_16x16x32_bf16 v[62:65], v[158:161], v[174:177], v[62:65]
	v_mfma_f32_16x16x32_bf16 v[58:61], v[166:169], v[174:177], v[58:61]
	v_mfma_f32_16x16x32_bf16 v[54:57], v[158:161], v[182:185], v[54:57]
	v_mfma_f32_16x16x32_bf16 v[46:49], v[166:169], v[182:185], v[46:49]
	v_mfma_f32_16x16x32_bf16 v[38:41], v[158:161], v[190:193], v[38:41]
	v_mfma_f32_16x16x32_bf16 v[30:33], v[166:169], v[190:193], v[30:33]
	v_mfma_f32_16x16x32_bf16 v[22:25], v[158:161], v[198:201], v[22:25]
	v_mfma_f32_16x16x32_bf16 v[14:17], v[166:169], v[198:201], v[14:17]
	v_mfma_f32_16x16x32_bf16 v[50:53], v[202:205], v[170:173], v[50:53]
	v_mfma_f32_16x16x32_bf16 v[42:45], v[210:213], v[170:173], v[42:45]
	v_mfma_f32_16x16x32_bf16 v[34:37], v[202:205], v[178:181], v[34:37]
	v_mfma_f32_16x16x32_bf16 v[26:29], v[210:213], v[178:181], v[26:29]
	v_mfma_f32_16x16x32_bf16 v[18:21], v[202:205], v[186:189], v[18:21]
	v_mfma_f32_16x16x32_bf16 v[10:13], v[210:213], v[186:189], v[10:13]
	v_mfma_f32_16x16x32_bf16 v[6:9], v[202:205], v[194:197], v[6:9]
	v_mfma_f32_16x16x32_bf16 v[2:5], v[210:213], v[194:197], v[2:5]
	v_mfma_f32_16x16x32_bf16 v[50:53], v[206:209], v[174:177], v[50:53]
	v_mfma_f32_16x16x32_bf16 v[42:45], v[214:217], v[174:177], v[42:45]
	v_mfma_f32_16x16x32_bf16 v[34:37], v[206:209], v[182:185], v[34:37]
	v_mfma_f32_16x16x32_bf16 v[26:29], v[214:217], v[182:185], v[26:29]
	v_mfma_f32_16x16x32_bf16 v[18:21], v[206:209], v[190:193], v[18:21]
	v_mfma_f32_16x16x32_bf16 v[10:13], v[214:217], v[190:193], v[10:13]
	v_mfma_f32_16x16x32_bf16 v[6:9], v[206:209], v[198:201], v[6:9]
	v_mfma_f32_16x16x32_bf16 v[2:5], v[214:217], v[198:201], v[2:5]
	s_setprio 0
	s_add_i32 s73, 0, 0x18000
	v_add_u32_e32 v153, s73, v148
	s_barrier
	ds_read_b128 v[154:157], v153
	ds_read_b128 v[158:161], v153 offset:1024
	ds_read_b128 v[162:165], v153 offset:2048
	ds_read_b128 v[166:169], v153 offset:3072
	ds_read_b128 v[202:205], v153 offset:16384
	ds_read_b128 v[206:209], v153 offset:17408
	ds_read_b128 v[210:213], v153 offset:18432
	ds_read_b128 v[214:217], v153 offset:19456
	s_add_u32 s28, s44, 0x100000
	s_addc_u32 s29, s45, 0
	s_mov_b32 m0, s55
	v_lshl_add_u64 v[226:227], s[28:29], 0, v[136:137]
	ds_read_b128 v[170:173], v151 offset:32768
	ds_read_b128 v[174:177], v151 offset:33792
	ds_read_b128 v[178:181], v151 offset:34816
	ds_read_b128 v[182:185], v151 offset:35840
	ds_read_b128 v[186:189], v151 offset:36864
	ds_read_b128 v[190:193], v151 offset:37888
	ds_read_b128 v[194:197], v151 offset:38912
	ds_read_b128 v[198:201], v151 offset:39936
	global_load_lds_dwordx4 v[226:227], off
	v_lshl_add_u64 v[226:227], s[28:29], 0, v[132:133]
	s_mov_b32 m0, s56
	s_nop 0
	global_load_lds_dwordx4 v[226:227], off
	s_waitcnt vmcnt(8)
	s_waitcnt lgkmcnt(0)
	s_barrier
	s_setprio 1
	v_mfma_f32_16x16x32_bf16 v[126:129], v[154:157], v[170:173], v[126:129]
	v_mfma_f32_16x16x32_bf16 v[122:125], v[162:165], v[170:173], v[122:125]
	v_mfma_f32_16x16x32_bf16 v[118:121], v[154:157], v[178:181], v[118:121]
	v_mfma_f32_16x16x32_bf16 v[110:113], v[162:165], v[178:181], v[110:113]
	v_mfma_f32_16x16x32_bf16 v[102:105], v[154:157], v[186:189], v[102:105]
	v_mfma_f32_16x16x32_bf16 v[94:97], v[162:165], v[186:189], v[94:97]
	v_mfma_f32_16x16x32_bf16 v[86:89], v[154:157], v[194:197], v[86:89]
	v_mfma_f32_16x16x32_bf16 v[78:81], v[162:165], v[194:197], v[78:81]
	v_mfma_f32_16x16x32_bf16 v[126:129], v[158:161], v[174:177], v[126:129]
	v_mfma_f32_16x16x32_bf16 v[122:125], v[166:169], v[174:177], v[122:125]
	v_mfma_f32_16x16x32_bf16 v[118:121], v[158:161], v[182:185], v[118:121]
	v_mfma_f32_16x16x32_bf16 v[110:113], v[166:169], v[182:185], v[110:113]
	v_mfma_f32_16x16x32_bf16 v[102:105], v[158:161], v[190:193], v[102:105]
	v_mfma_f32_16x16x32_bf16 v[94:97], v[166:169], v[190:193], v[94:97]
	v_mfma_f32_16x16x32_bf16 v[86:89], v[158:161], v[198:201], v[86:89]
	v_mfma_f32_16x16x32_bf16 v[78:81], v[166:169], v[198:201], v[78:81]
	v_mfma_f32_16x16x32_bf16 v[114:117], v[202:205], v[170:173], v[114:117]
	v_mfma_f32_16x16x32_bf16 v[106:109], v[210:213], v[170:173], v[106:109]
	v_mfma_f32_16x16x32_bf16 v[98:101], v[202:205], v[178:181], v[98:101]
	v_mfma_f32_16x16x32_bf16 v[90:93], v[210:213], v[178:181], v[90:93]
	v_mfma_f32_16x16x32_bf16 v[82:85], v[202:205], v[186:189], v[82:85]
	v_mfma_f32_16x16x32_bf16 v[74:77], v[210:213], v[186:189], v[74:77]
	v_mfma_f32_16x16x32_bf16 v[70:73], v[202:205], v[194:197], v[70:73]
	v_mfma_f32_16x16x32_bf16 v[66:69], v[210:213], v[194:197], v[66:69]
	v_mfma_f32_16x16x32_bf16 v[114:117], v[206:209], v[174:177], v[114:117]
	v_mfma_f32_16x16x32_bf16 v[106:109], v[214:217], v[174:177], v[106:109]
	v_mfma_f32_16x16x32_bf16 v[98:101], v[206:209], v[182:185], v[98:101]
	v_mfma_f32_16x16x32_bf16 v[90:93], v[214:217], v[182:185], v[90:93]
	v_mfma_f32_16x16x32_bf16 v[82:85], v[206:209], v[190:193], v[82:85]
	v_mfma_f32_16x16x32_bf16 v[74:77], v[214:217], v[190:193], v[74:77]
	v_mfma_f32_16x16x32_bf16 v[70:73], v[206:209], v[198:201], v[70:73]
	v_mfma_f32_16x16x32_bf16 v[66:69], v[214:217], v[198:201], v[66:69]
	s_setprio 0
	s_barrier
	ds_read_b128 v[170:173], v151 offset:49152
	ds_read_b128 v[174:177], v151 offset:50176
	ds_read_b128 v[178:181], v151 offset:51200
	ds_read_b128 v[182:185], v151 offset:52224
	ds_read_b128 v[186:189], v151 offset:53248
	ds_read_b128 v[190:193], v151 offset:54272
	ds_read_b128 v[194:197], v151 offset:55296
	ds_read_b128 v[198:201], v151 offset:56320
	s_add_i32 s44, 0, 0x1c000
	s_add_i32 s28, s73, s54
	v_lshl_add_u64 v[146:147], v[146:147], 0, s[6:7]
	s_mov_b32 m0, s28
	s_nop 0
	global_load_lds_dwordx4 v[146:147], off
	v_lshl_add_u64 v[146:147], v[218:219], 0, s[6:7]
	s_add_i32 m0, s28, 0x2000
	s_nop 0
	global_load_lds_dwordx4 v[146:147], off
	s_mov_b32 m0, s59
	v_lshl_add_u64 v[146:147], v[220:221], 0, s[6:7]
	global_load_lds_dwordx4 v[146:147], off
	v_lshl_add_u64 v[146:147], v[222:223], 0, s[6:7]
	s_mov_b32 m0, s60
	s_nop 0
	global_load_lds_dwordx4 v[146:147], off
	s_add_u32 s28, s40, 0x100080
	s_addc_u32 s29, s41, 0
	s_add_i32 s40, s44, s54
	v_lshl_add_u64 v[146:147], s[28:29], 0, v[134:135]
	s_mov_b32 m0, s40
	s_nop 0
	global_load_lds_dwordx4 v[146:147], off
	v_lshl_add_u64 v[146:147], s[28:29], 0, v[130:131]
	s_add_i32 m0, s40, 0x2000
	s_nop 0
	global_load_lds_dwordx4 v[146:147], off
	s_waitcnt vmcnt(8)
	s_waitcnt lgkmcnt(0)
	s_barrier
	s_setprio 1
	v_mfma_f32_16x16x32_bf16 v[62:65], v[154:157], v[170:173], v[62:65]
	v_mfma_f32_16x16x32_bf16 v[58:61], v[162:165], v[170:173], v[58:61]
	v_mfma_f32_16x16x32_bf16 v[54:57], v[154:157], v[178:181], v[54:57]
	v_mfma_f32_16x16x32_bf16 v[46:49], v[162:165], v[178:181], v[46:49]
	v_mfma_f32_16x16x32_bf16 v[38:41], v[154:157], v[186:189], v[38:41]
	v_mfma_f32_16x16x32_bf16 v[30:33], v[162:165], v[186:189], v[30:33]
	v_mfma_f32_16x16x32_bf16 v[22:25], v[154:157], v[194:197], v[22:25]
	v_mfma_f32_16x16x32_bf16 v[14:17], v[162:165], v[194:197], v[14:17]
	v_mfma_f32_16x16x32_bf16 v[62:65], v[158:161], v[174:177], v[62:65]
	v_mfma_f32_16x16x32_bf16 v[58:61], v[166:169], v[174:177], v[58:61]
	v_mfma_f32_16x16x32_bf16 v[54:57], v[158:161], v[182:185], v[54:57]
	v_mfma_f32_16x16x32_bf16 v[46:49], v[166:169], v[182:185], v[46:49]
	v_mfma_f32_16x16x32_bf16 v[38:41], v[158:161], v[190:193], v[38:41]
	v_mfma_f32_16x16x32_bf16 v[30:33], v[166:169], v[190:193], v[30:33]
	v_mfma_f32_16x16x32_bf16 v[22:25], v[158:161], v[198:201], v[22:25]
	v_mfma_f32_16x16x32_bf16 v[14:17], v[166:169], v[198:201], v[14:17]
	v_mfma_f32_16x16x32_bf16 v[50:53], v[202:205], v[170:173], v[50:53]
	v_mfma_f32_16x16x32_bf16 v[42:45], v[210:213], v[170:173], v[42:45]
	v_mfma_f32_16x16x32_bf16 v[34:37], v[202:205], v[178:181], v[34:37]
	v_mfma_f32_16x16x32_bf16 v[26:29], v[210:213], v[178:181], v[26:29]
	v_mfma_f32_16x16x32_bf16 v[18:21], v[202:205], v[186:189], v[18:21]
	v_mfma_f32_16x16x32_bf16 v[10:13], v[210:213], v[186:189], v[10:13]
	v_mfma_f32_16x16x32_bf16 v[6:9], v[202:205], v[194:197], v[6:9]
	v_mfma_f32_16x16x32_bf16 v[2:5], v[210:213], v[194:197], v[2:5]
	v_mfma_f32_16x16x32_bf16 v[50:53], v[206:209], v[174:177], v[50:53]
	v_mfma_f32_16x16x32_bf16 v[42:45], v[214:217], v[174:177], v[42:45]
	v_mfma_f32_16x16x32_bf16 v[34:37], v[206:209], v[182:185], v[34:37]
	v_mfma_f32_16x16x32_bf16 v[26:29], v[214:217], v[182:185], v[26:29]
	v_mfma_f32_16x16x32_bf16 v[18:21], v[206:209], v[190:193], v[18:21]
	v_mfma_f32_16x16x32_bf16 v[10:13], v[214:217], v[190:193], v[10:13]
	v_mfma_f32_16x16x32_bf16 v[6:9], v[206:209], v[198:201], v[6:9]
	v_mfma_f32_16x16x32_bf16 v[2:5], v[214:217], v[198:201], v[2:5]
	s_setprio 0
	s_add_i32 s72, s72, 2
	s_add_u32 s21, s21, 0x100
	s_addc_u32 s71, s71, 0
	s_add_u32 s38, s38, 0x100
	s_addc_u32 s39, s39, 0
	s_cmp_gt_u32 s72, 61
	s_barrier
	s_cbranch_scc0 .LBB0_3048
	s_waitcnt vmcnt(6)
	s_cmp_lt_i32 s70, 2
	s_cbranch_scc1 .LBB0_3053
	s_cmp_eq_u32 s70, 2
	s_mov_b64 s[38:39], -1
	s_cbranch_scc0 .LBB0_3052
	v_lshl_add_u32 v146, s26, 8, v1
	v_or_b32_e32 v156, 16, v146
	v_ashrrev_i32_e32 v147, 31, v146
	v_ashrrev_i32_e32 v157, 31, v156
	v_lshlrev_b64 v[154:155], 10, v[146:147]
	v_lshlrev_b64 v[156:157], 10, v[156:157]
	v_lshl_add_u64 v[154:155], v[138:139], 0, v[154:155]
	v_lshl_add_u64 v[156:157], v[138:139], 0, v[156:157]
	global_store_dwordx4 v[154:155], v[126:129], off
	global_store_dwordx4 v[154:155], v[122:125], off offset:16
	global_store_dwordx4 v[154:155], v[114:117], off offset:512
	global_store_dwordx4 v[154:155], v[106:109], off offset:528
	global_store_dwordx4 v[156:157], v[118:121], off
	global_store_dwordx4 v[156:157], v[110:113], off offset:16
	global_store_dwordx4 v[156:157], v[98:101], off offset:512
	global_store_dwordx4 v[156:157], v[90:93], off offset:528
	v_or_b32_e32 v156, 32, v146
	v_ashrrev_i32_e32 v157, 31, v156
	v_lshlrev_b64 v[156:157], 10, v[156:157]
	v_or_b32_e32 v146, 48, v146
	v_lshl_add_u64 v[156:157], v[138:139], 0, v[156:157]
	v_ashrrev_i32_e32 v147, 31, v146
	global_store_dwordx4 v[156:157], v[102:105], off
	global_store_dwordx4 v[156:157], v[94:97], off offset:16
	global_store_dwordx4 v[156:157], v[82:85], off offset:512
	global_store_dwordx4 v[156:157], v[74:77], off offset:528
	v_lshlrev_b64 v[146:147], 10, v[146:147]
	v_add_co_u32_e32 v156, vcc, s66, v154
	v_lshl_add_u64 v[146:147], v[138:139], 0, v[146:147]
	s_nop 0
	v_addc_co_u32_e32 v157, vcc, 0, v155, vcc
	global_store_dwordx4 v[146:147], v[86:89], off
	global_store_dwordx4 v[146:147], v[78:81], off offset:16
	global_store_dwordx4 v[146:147], v[70:73], off offset:512
	global_store_dwordx4 v[146:147], v[66:69], off offset:528
	v_lshl_add_u64 v[146:147], v[154:155], 0, s[8:9]
	global_store_dwordx4 v[156:157], v[62:65], off
	global_store_dwordx4 v[146:147], v[58:61], off offset:16
	global_store_dwordx4 v[146:147], v[50:53], off offset:512
	global_store_dwordx4 v[146:147], v[42:45], off offset:528
	v_add_co_u32_e32 v156, vcc, s67, v154
	v_lshl_add_u64 v[146:147], v[154:155], 0, s[12:13]
	s_nop 0
	v_addc_co_u32_e32 v157, vcc, 0, v155, vcc
	global_store_dwordx4 v[156:157], v[54:57], off
	global_store_dwordx4 v[146:147], v[46:49], off offset:16
	global_store_dwordx4 v[146:147], v[34:37], off offset:512
	global_store_dwordx4 v[146:147], v[26:29], off offset:528
	v_add_co_u32_e32 v156, vcc, s68, v154
	v_lshl_add_u64 v[146:147], v[154:155], 0, s[14:15]
	s_nop 0
	v_addc_co_u32_e32 v157, vcc, 0, v155, vcc
	global_store_dwordx4 v[156:157], v[38:41], off
	global_store_dwordx4 v[146:147], v[30:33], off offset:16
	global_store_dwordx4 v[146:147], v[18:21], off offset:512
	global_store_dwordx4 v[146:147], v[10:13], off offset:528
	v_lshl_add_u64 v[146:147], v[154:155], 0, s[16:17]
	v_add_co_u32_e32 v154, vcc, 0x2c000, v154
	s_mov_b64 s[38:39], 0
	s_nop 0
	v_addc_co_u32_e32 v155, vcc, 0, v155, vcc
	global_store_dwordx4 v[154:155], v[22:25], off
	global_store_dwordx4 v[146:147], v[14:17], off offset:16
	global_store_dwordx4 v[146:147], v[6:9], off offset:512
	global_store_dwordx4 v[146:147], v[2:5], off offset:528

.LBB0_4133:
	ds_read_b128 v[152:155], v148
	ds_read_b128 v[156:159], v148 offset:1024
	ds_read_b128 v[160:163], v148 offset:2048
	ds_read_b128 v[164:167], v148 offset:3072
	ds_read_b128 v[200:203], v150
	ds_read_b128 v[204:207], v150 offset:1024
	ds_read_b128 v[208:211], v150 offset:2048
	ds_read_b128 v[212:215], v150 offset:3072
	s_add_u32 s28, s38, 0xfff00080
	s_addc_u32 s29, s39, -1
	s_cmp_eq_u32 s60, 60
	s_cselect_b32 s45, s27, s29
	s_cselect_b32 s44, s26, s28
	s_cselect_b32 s41, s35, s23
	s_cselect_b32 s40, s34, s21
	v_lshl_add_u64 v[144:145], s[38:39], 0, v[140:141]
	s_add_i32 m0, s37, 0xc000
	ds_read_b128 v[168:171], v149
	ds_read_b128 v[172:175], v149 offset:1024
	ds_read_b128 v[176:179], v149 offset:2048
	ds_read_b128 v[180:183], v149 offset:3072
	ds_read_b128 v[184:187], v149 offset:4096
	ds_read_b128 v[188:191], v149 offset:5120
	ds_read_b128 v[192:195], v149 offset:6144
	ds_read_b128 v[196:199], v149 offset:7168
	global_load_lds_dwordx4 v[144:145], off
	v_lshl_add_u64 v[144:145], s[38:39], 0, v[138:139]
	s_add_i32 m0, s37, 0xe000
	s_nop 0
	global_load_lds_dwordx4 v[144:145], off
	s_cmp_eq_u32 s60, -2
	s_cbranch_scc1 .Lk2_skip_4133
	s_waitcnt vmcnt(8)
.Lk2_skip_4133:
	s_waitcnt lgkmcnt(0)
	s_barrier
	s_setprio 1
	v_mfma_f32_16x16x32_bf16 v[126:129], v[152:155], v[168:171], v[126:129]
	v_mfma_f32_16x16x32_bf16 v[122:125], v[160:163], v[168:171], v[122:125]
	v_mfma_f32_16x16x32_bf16 v[114:117], v[152:155], v[176:179], v[114:117]
	v_mfma_f32_16x16x32_bf16 v[106:109], v[160:163], v[176:179], v[106:109]
	v_mfma_f32_16x16x32_bf16 v[98:101], v[152:155], v[184:187], v[98:101]
	v_mfma_f32_16x16x32_bf16 v[90:93], v[160:163], v[184:187], v[90:93]
	v_mfma_f32_16x16x32_bf16 v[82:85], v[152:155], v[192:195], v[82:85]
	v_mfma_f32_16x16x32_bf16 v[74:77], v[160:163], v[192:195], v[74:77]
	v_mfma_f32_16x16x32_bf16 v[126:129], v[156:159], v[172:175], v[126:129]
	v_mfma_f32_16x16x32_bf16 v[122:125], v[164:167], v[172:175], v[122:125]
	v_mfma_f32_16x16x32_bf16 v[114:117], v[156:159], v[180:183], v[114:117]
	v_mfma_f32_16x16x32_bf16 v[106:109], v[164:167], v[180:183], v[106:109]
	v_mfma_f32_16x16x32_bf16 v[98:101], v[156:159], v[188:191], v[98:101]
	v_mfma_f32_16x16x32_bf16 v[90:93], v[164:167], v[188:191], v[90:93]
	v_mfma_f32_16x16x32_bf16 v[82:85], v[156:159], v[196:199], v[82:85]
	v_mfma_f32_16x16x32_bf16 v[74:77], v[164:167], v[196:199], v[74:77]
	v_mfma_f32_16x16x32_bf16 v[118:121], v[200:203], v[168:171], v[118:121]
	v_mfma_f32_16x16x32_bf16 v[110:113], v[208:211], v[168:171], v[110:113]
	v_mfma_f32_16x16x32_bf16 v[102:105], v[200:203], v[176:179], v[102:105]
	v_mfma_f32_16x16x32_bf16 v[94:97], v[208:211], v[176:179], v[94:97]
	v_mfma_f32_16x16x32_bf16 v[86:89], v[200:203], v[184:187], v[86:89]
	v_mfma_f32_16x16x32_bf16 v[78:81], v[208:211], v[184:187], v[78:81]
	v_mfma_f32_16x16x32_bf16 v[70:73], v[200:203], v[192:195], v[70:73]
	v_mfma_f32_16x16x32_bf16 v[66:69], v[208:211], v[192:195], v[66:69]
	v_mfma_f32_16x16x32_bf16 v[118:121], v[204:207], v[172:175], v[118:121]
	v_mfma_f32_16x16x32_bf16 v[110:113], v[212:215], v[172:175], v[110:113]
	v_mfma_f32_16x16x32_bf16 v[102:105], v[204:207], v[180:183], v[102:105]
	v_mfma_f32_16x16x32_bf16 v[94:97], v[212:215], v[180:183], v[94:97]
	v_mfma_f32_16x16x32_bf16 v[86:89], v[204:207], v[188:191], v[86:89]
	v_mfma_f32_16x16x32_bf16 v[78:81], v[212:215], v[188:191], v[78:81]
	v_mfma_f32_16x16x32_bf16 v[70:73], v[204:207], v[196:199], v[70:73]
	v_mfma_f32_16x16x32_bf16 v[66:69], v[212:215], v[196:199], v[66:69]
	s_setprio 0
	s_barrier
	ds_read_b128 v[168:171], v149 offset:16384
	ds_read_b128 v[172:175], v149 offset:17408
	ds_read_b128 v[176:179], v149 offset:18432
	ds_read_b128 v[180:183], v149 offset:19456
	ds_read_b128 v[184:187], v149 offset:20480
	ds_read_b128 v[188:191], v149 offset:21504
	ds_read_b128 v[192:195], v149 offset:22528
	ds_read_b128 v[196:199], v149 offset:23552
	s_add_i32 s28, s53, s31
	v_lshl_add_u64 v[144:145], s[40:41], 0, v[134:135]
	s_mov_b32 m0, s28
	s_nop 0
	global_load_lds_dwordx4 v[144:145], off
	v_lshl_add_u64 v[216:217], s[40:41], 0, v[130:131]
	s_add_i32 m0, s28, 0x2000
	s_nop 0
	global_load_lds_dwordx4 v[216:217], off
	s_mov_b32 m0, s37
	v_lshl_add_u64 v[218:219], s[44:45], 0, v[136:137]
	global_load_lds_dwordx4 v[218:219], off
	v_lshl_add_u64 v[220:221], s[44:45], 0, v[132:133]
	s_mov_b32 m0, s46
	s_nop 0
	global_load_lds_dwordx4 v[220:221], off
	s_add_u32 s28, s40, 0x100000
	s_addc_u32 s29, s41, 0
	s_add_i32 s61, s54, s31
	v_lshl_add_u64 v[226:227], s[28:29], 0, v[134:135]
	s_mov_b32 m0, s61
	s_nop 0
	global_load_lds_dwordx4 v[226:227], off
	v_lshl_add_u64 v[226:227], s[28:29], 0, v[130:131]
	s_add_i32 m0, s61, 0x2000
	s_nop 0
	global_load_lds_dwordx4 v[226:227], off
	s_waitcnt vmcnt(8)
	s_waitcnt lgkmcnt(0)
	s_barrier
	s_setprio 1
	v_mfma_f32_16x16x32_bf16 v[62:65], v[152:155], v[168:171], v[62:65]
	v_mfma_f32_16x16x32_bf16 v[58:61], v[160:163], v[168:171], v[58:61]
	v_mfma_f32_16x16x32_bf16 v[54:57], v[152:155], v[176:179], v[54:57]
	v_mfma_f32_16x16x32_bf16 v[46:49], v[160:163], v[176:179], v[46:49]
	v_mfma_f32_16x16x32_bf16 v[38:41], v[152:155], v[184:187], v[38:41]
	v_mfma_f32_16x16x32_bf16 v[30:33], v[160:163], v[184:187], v[30:33]
	v_mfma_f32_16x16x32_bf16 v[22:25], v[152:155], v[192:195], v[22:25]
	v_mfma_f32_16x16x32_bf16 v[14:17], v[160:163], v[192:195], v[14:17]
	v_mfma_f32_16x16x32_bf16 v[62:65], v[156:159], v[172:175], v[62:65]
	v_mfma_f32_16x16x32_bf16 v[58:61], v[164:167], v[172:175], v[58:61]
	v_mfma_f32_16x16x32_bf16 v[54:57], v[156:159], v[180:183], v[54:57]
	v_mfma_f32_16x16x32_bf16 v[46:49], v[164:167], v[180:183], v[46:49]
	v_mfma_f32_16x16x32_bf16 v[38:41], v[156:159], v[188:191], v[38:41]
	v_mfma_f32_16x16x32_bf16 v[30:33], v[164:167], v[188:191], v[30:33]
	v_mfma_f32_16x16x32_bf16 v[22:25], v[156:159], v[196:199], v[22:25]
	v_mfma_f32_16x16x32_bf16 v[14:17], v[164:167], v[196:199], v[14:17]
	v_mfma_f32_16x16x32_bf16 v[50:53], v[200:203], v[168:171], v[50:53]
	v_mfma_f32_16x16x32_bf16 v[42:45], v[208:211], v[168:171], v[42:45]
	v_mfma_f32_16x16x32_bf16 v[34:37], v[200:203], v[176:179], v[34:37]
	v_mfma_f32_16x16x32_bf16 v[26:29], v[208:211], v[176:179], v[26:29]
	v_mfma_f32_16x16x32_bf16 v[18:21], v[200:203], v[184:187], v[18:21]
	v_mfma_f32_16x16x32_bf16 v[10:13], v[208:211], v[184:187], v[10:13]
	v_mfma_f32_16x16x32_bf16 v[6:9], v[200:203], v[192:195], v[6:9]
	v_mfma_f32_16x16x32_bf16 v[2:5], v[208:211], v[192:195], v[2:5]
	v_mfma_f32_16x16x32_bf16 v[50:53], v[204:207], v[172:175], v[50:53]
	v_mfma_f32_16x16x32_bf16 v[42:45], v[212:215], v[172:175], v[42:45]
	v_mfma_f32_16x16x32_bf16 v[34:37], v[204:207], v[180:183], v[34:37]
	v_mfma_f32_16x16x32_bf16 v[26:29], v[212:215], v[180:183], v[26:29]
	v_mfma_f32_16x16x32_bf16 v[18:21], v[204:207], v[188:191], v[18:21]
	v_mfma_f32_16x16x32_bf16 v[10:13], v[212:215], v[188:191], v[10:13]
	v_mfma_f32_16x16x32_bf16 v[6:9], v[204:207], v[196:199], v[6:9]
	v_mfma_f32_16x16x32_bf16 v[2:5], v[212:215], v[196:199], v[2:5]
	s_setprio 0
	s_add_i32 s61, 0, 0x18000
	v_add_u32_e32 v151, s61, v146
	s_barrier
	ds_read_b128 v[152:155], v151
	ds_read_b128 v[156:159], v151 offset:1024
	ds_read_b128 v[160:163], v151 offset:2048
	ds_read_b128 v[164:167], v151 offset:3072
	ds_read_b128 v[200:203], v151 offset:16384
	ds_read_b128 v[204:207], v151 offset:17408
	ds_read_b128 v[208:211], v151 offset:18432
	ds_read_b128 v[212:215], v151 offset:19456
	s_add_u32 s28, s44, 0x100000
	s_addc_u32 s29, s45, 0
	s_mov_b32 m0, s47
	v_lshl_add_u64 v[226:227], s[28:29], 0, v[136:137]
	ds_read_b128 v[168:171], v149 offset:32768
	ds_read_b128 v[172:175], v149 offset:33792
	ds_read_b128 v[176:179], v149 offset:34816
	ds_read_b128 v[180:183], v149 offset:35840
	ds_read_b128 v[184:187], v149 offset:36864
	ds_read_b128 v[188:191], v149 offset:37888
	ds_read_b128 v[192:195], v149 offset:38912
	ds_read_b128 v[196:199], v149 offset:39936
	global_load_lds_dwordx4 v[226:227], off
	v_lshl_add_u64 v[226:227], s[28:29], 0, v[132:133]
	s_mov_b32 m0, s48
	s_nop 0
	global_load_lds_dwordx4 v[226:227], off
	s_waitcnt vmcnt(8)
	s_waitcnt lgkmcnt(0)
	s_barrier
	s_setprio 1
	v_mfma_f32_16x16x32_bf16 v[126:129], v[152:155], v[168:171], v[126:129]
	v_mfma_f32_16x16x32_bf16 v[122:125], v[160:163], v[168:171], v[122:125]
	v_mfma_f32_16x16x32_bf16 v[114:117], v[152:155], v[176:179], v[114:117]
	v_mfma_f32_16x16x32_bf16 v[106:109], v[160:163], v[176:179], v[106:109]
	v_mfma_f32_16x16x32_bf16 v[98:101], v[152:155], v[184:187], v[98:101]
	v_mfma_f32_16x16x32_bf16 v[90:93], v[160:163], v[184:187], v[90:93]
	v_mfma_f32_16x16x32_bf16 v[82:85], v[152:155], v[192:195], v[82:85]
	v_mfma_f32_16x16x32_bf16 v[74:77], v[160:163], v[192:195], v[74:77]
	v_mfma_f32_16x16x32_bf16 v[126:129], v[156:159], v[172:175], v[126:129]
	v_mfma_f32_16x16x32_bf16 v[122:125], v[164:167], v[172:175], v[122:125]
	v_mfma_f32_16x16x32_bf16 v[114:117], v[156:159], v[180:183], v[114:117]
	v_mfma_f32_16x16x32_bf16 v[106:109], v[164:167], v[180:183], v[106:109]
	v_mfma_f32_16x16x32_bf16 v[98:101], v[156:159], v[188:191], v[98:101]
	v_mfma_f32_16x16x32_bf16 v[90:93], v[164:167], v[188:191], v[90:93]
	v_mfma_f32_16x16x32_bf16 v[82:85], v[156:159], v[196:199], v[82:85]
	v_mfma_f32_16x16x32_bf16 v[74:77], v[164:167], v[196:199], v[74:77]
	v_mfma_f32_16x16x32_bf16 v[118:121], v[200:203], v[168:171], v[118:121]
	v_mfma_f32_16x16x32_bf16 v[110:113], v[208:211], v[168:171], v[110:113]
	v_mfma_f32_16x16x32_bf16 v[102:105], v[200:203], v[176:179], v[102:105]
	v_mfma_f32_16x16x32_bf16 v[94:97], v[208:211], v[176:179], v[94:97]
	v_mfma_f32_16x16x32_bf16 v[86:89], v[200:203], v[184:187], v[86:89]
	v_mfma_f32_16x16x32_bf16 v[78:81], v[208:211], v[184:187], v[78:81]
	v_mfma_f32_16x16x32_bf16 v[70:73], v[200:203], v[192:195], v[70:73]
	v_mfma_f32_16x16x32_bf16 v[66:69], v[208:211], v[192:195], v[66:69]
	v_mfma_f32_16x16x32_bf16 v[118:121], v[204:207], v[172:175], v[118:121]
	v_mfma_f32_16x16x32_bf16 v[110:113], v[212:215], v[172:175], v[110:113]
	v_mfma_f32_16x16x32_bf16 v[102:105], v[204:207], v[180:183], v[102:105]
	v_mfma_f32_16x16x32_bf16 v[94:97], v[212:215], v[180:183], v[94:97]
	v_mfma_f32_16x16x32_bf16 v[86:89], v[204:207], v[188:191], v[86:89]
	v_mfma_f32_16x16x32_bf16 v[78:81], v[212:215], v[188:191], v[78:81]
	v_mfma_f32_16x16x32_bf16 v[70:73], v[204:207], v[196:199], v[70:73]
	v_mfma_f32_16x16x32_bf16 v[66:69], v[212:215], v[196:199], v[66:69]
	s_setprio 0
	s_barrier
	ds_read_b128 v[168:171], v149 offset:49152
	ds_read_b128 v[172:175], v149 offset:50176
	ds_read_b128 v[176:179], v149 offset:51200
	ds_read_b128 v[180:183], v149 offset:52224
	ds_read_b128 v[184:187], v149 offset:53248
	ds_read_b128 v[188:191], v149 offset:54272
	ds_read_b128 v[192:195], v149 offset:55296
	ds_read_b128 v[196:199], v149 offset:56320
	s_add_i32 s44, 0, 0x1c000
	s_add_i32 s28, s61, s31
	v_lshl_add_u64 v[144:145], v[144:145], 0, s[12:13]
	s_mov_b32 m0, s28
	s_nop 0
	global_load_lds_dwordx4 v[144:145], off
	v_lshl_add_u64 v[144:145], v[216:217], 0, s[12:13]
	s_add_i32 m0, s28, 0x2000
	s_nop 0
	global_load_lds_dwordx4 v[144:145], off
	s_mov_b32 m0, s50
	v_lshl_add_u64 v[144:145], v[218:219], 0, s[12:13]
	global_load_lds_dwordx4 v[144:145], off
	v_lshl_add_u64 v[144:145], v[220:221], 0, s[12:13]
	s_mov_b32 m0, s51
	s_nop 0
	global_load_lds_dwordx4 v[144:145], off
	s_add_u32 s28, s40, 0x100080
	s_addc_u32 s29, s41, 0
	s_add_i32 s40, s44, s31
	v_lshl_add_u64 v[144:145], s[28:29], 0, v[134:135]
	s_mov_b32 m0, s40
	s_nop 0
	global_load_lds_dwordx4 v[144:145], off
	v_lshl_add_u64 v[144:145], s[28:29], 0, v[130:131]
	s_add_i32 m0, s40, 0x2000
	s_nop 0
	global_load_lds_dwordx4 v[144:145], off
	s_waitcnt vmcnt(8)
	s_waitcnt lgkmcnt(0)
	s_barrier
	s_setprio 1
	v_mfma_f32_16x16x32_bf16 v[62:65], v[152:155], v[168:171], v[62:65]
	v_mfma_f32_16x16x32_bf16 v[58:61], v[160:163], v[168:171], v[58:61]
	v_mfma_f32_16x16x32_bf16 v[54:57], v[152:155], v[176:179], v[54:57]
	v_mfma_f32_16x16x32_bf16 v[46:49], v[160:163], v[176:179], v[46:49]
	v_mfma_f32_16x16x32_bf16 v[38:41], v[152:155], v[184:187], v[38:41]
	v_mfma_f32_16x16x32_bf16 v[30:33], v[160:163], v[184:187], v[30:33]
	v_mfma_f32_16x16x32_bf16 v[22:25], v[152:155], v[192:195], v[22:25]
	v_mfma_f32_16x16x32_bf16 v[14:17], v[160:163], v[192:195], v[14:17]
	v_mfma_f32_16x16x32_bf16 v[62:65], v[156:159], v[172:175], v[62:65]
	v_mfma_f32_16x16x32_bf16 v[58:61], v[164:167], v[172:175], v[58:61]
	v_mfma_f32_16x16x32_bf16 v[54:57], v[156:159], v[180:183], v[54:57]
	v_mfma_f32_16x16x32_bf16 v[46:49], v[164:167], v[180:183], v[46:49]
	v_mfma_f32_16x16x32_bf16 v[38:41], v[156:159], v[188:191], v[38:41]
	v_mfma_f32_16x16x32_bf16 v[30:33], v[164:167], v[188:191], v[30:33]
	v_mfma_f32_16x16x32_bf16 v[22:25], v[156:159], v[196:199], v[22:25]
	v_mfma_f32_16x16x32_bf16 v[14:17], v[164:167], v[196:199], v[14:17]
	v_mfma_f32_16x16x32_bf16 v[50:53], v[200:203], v[168:171], v[50:53]
	v_mfma_f32_16x16x32_bf16 v[42:45], v[208:211], v[168:171], v[42:45]
	v_mfma_f32_16x16x32_bf16 v[34:37], v[200:203], v[176:179], v[34:37]
	v_mfma_f32_16x16x32_bf16 v[26:29], v[208:211], v[176:179], v[26:29]
	v_mfma_f32_16x16x32_bf16 v[18:21], v[200:203], v[184:187], v[18:21]
	v_mfma_f32_16x16x32_bf16 v[10:13], v[208:211], v[184:187], v[10:13]
	v_mfma_f32_16x16x32_bf16 v[6:9], v[200:203], v[192:195], v[6:9]
	v_mfma_f32_16x16x32_bf16 v[2:5], v[208:211], v[192:195], v[2:5]
	v_mfma_f32_16x16x32_bf16 v[50:53], v[204:207], v[172:175], v[50:53]
	v_mfma_f32_16x16x32_bf16 v[42:45], v[212:215], v[172:175], v[42:45]
	v_mfma_f32_16x16x32_bf16 v[34:37], v[204:207], v[180:183], v[34:37]
	v_mfma_f32_16x16x32_bf16 v[26:29], v[212:215], v[180:183], v[26:29]
	v_mfma_f32_16x16x32_bf16 v[18:21], v[204:207], v[188:191], v[18:21]
	v_mfma_f32_16x16x32_bf16 v[10:13], v[212:215], v[188:191], v[10:13]
	v_mfma_f32_16x16x32_bf16 v[6:9], v[204:207], v[196:199], v[6:9]
	v_mfma_f32_16x16x32_bf16 v[2:5], v[212:215], v[196:199], v[2:5]
	s_setprio 0
	s_add_i32 s60, s60, 2
	s_add_u32 s21, s21, 0x100
	s_addc_u32 s23, s23, 0
	s_add_u32 s38, s38, 0x100
	s_addc_u32 s39, s39, 0
	s_cmp_gt_u32 s60, 61
	s_barrier
	s_cbranch_scc0 .LBB0_4133
	s_waitcnt vmcnt(6)
	v_lshl_add_u32 v152, s36, 8, v1
	v_lshl_or_b32 v144, s59, 8, v147
	v_ashrrev_i32_e32 v153, 31, v152
	v_ashrrev_i32_e32 v145, 31, v144
	v_lshlrev_b64 v[154:155], 13, v[152:153]
	v_lshl_add_u64 v[154:155], s[8:9], 0, v[154:155]
	v_lshlrev_b64 v[156:157], 1, v[144:145]
	v_lshl_add_u64 v[144:145], v[154:155], 0, v[156:157]
	v_cvt_pk_bf16_f32 v126, v126, v127
	v_cvt_pk_bf16_f32 v127, v128, v129
	v_cvt_pk_bf16_f32 v128, v122, v123
	v_cvt_pk_bf16_f32 v129, v124, v125
	global_store_dwordx4 v[144:145], v[126:129], off
	v_cvt_pk_bf16_f32 v118, v118, v119
	v_cvt_pk_bf16_f32 v119, v120, v121
	v_cvt_pk_bf16_f32 v120, v110, v111
	v_or_b32_e32 v110, 16, v152
	v_ashrrev_i32_e32 v111, 31, v110
	v_lshlrev_b64 v[110:111], 13, v[110:111]
	v_lshl_add_u64 v[110:111], s[8:9], 0, v[110:111]
	v_cvt_pk_bf16_f32 v121, v112, v113
	global_store_dwordx4 v[144:145], v[118:121], off offset:256
	s_mov_b32 s36, s22
	s_mov_b32 s59, s20
	v_lshl_add_u64 v[118:119], v[110:111], 0, v[156:157]
	v_cvt_pk_bf16_f32 v110, v114, v115
	v_cvt_pk_bf16_f32 v111, v116, v117
	v_cvt_pk_bf16_f32 v112, v106, v107
	v_cvt_pk_bf16_f32 v113, v108, v109
	global_store_dwordx4 v[118:119], v[110:113], off
	v_cvt_pk_bf16_f32 v102, v102, v103
	v_cvt_pk_bf16_f32 v103, v104, v105
	v_cvt_pk_bf16_f32 v104, v94, v95
	v_or_b32_e32 v94, 32, v152
	v_ashrrev_i32_e32 v95, 31, v94
	v_lshlrev_b64 v[94:95], 13, v[94:95]
	v_lshl_add_u64 v[94:95], s[8:9], 0, v[94:95]
	v_cvt_pk_bf16_f32 v105, v96, v97
	global_store_dwordx4 v[118:119], v[102:105], off offset:256
	s_mov_b64 s[40:41], s[34:35]
	s_mov_b64 s[38:39], s[26:27]
	v_lshl_add_u64 v[102:103], v[94:95], 0, v[156:157]
	v_cvt_pk_bf16_f32 v94, v98, v99
	v_cvt_pk_bf16_f32 v95, v100, v101
	v_cvt_pk_bf16_f32 v96, v90, v91
	v_cvt_pk_bf16_f32 v97, v92, v93
	global_store_dwordx4 v[102:103], v[94:97], off
	v_cvt_pk_bf16_f32 v86, v86, v87
	v_cvt_pk_bf16_f32 v87, v88, v89
	v_cvt_pk_bf16_f32 v88, v78, v79
	v_or_b32_e32 v78, 48, v152
	v_ashrrev_i32_e32 v79, 31, v78
	v_lshlrev_b64 v[78:79], 13, v[78:79]
	v_lshl_add_u64 v[78:79], s[8:9], 0, v[78:79]
	v_cvt_pk_bf16_f32 v89, v80, v81
	global_store_dwordx4 v[102:103], v[86:89], off offset:256
	s_nop 1
	v_lshl_add_u64 v[86:87], v[78:79], 0, v[156:157]
	v_cvt_pk_bf16_f32 v78, v82, v83
	v_cvt_pk_bf16_f32 v79, v84, v85
	v_cvt_pk_bf16_f32 v80, v74, v75
	v_cvt_pk_bf16_f32 v81, v76, v77
	global_store_dwordx4 v[86:87], v[78:81], off
	v_cvt_pk_bf16_f32 v70, v70, v71
	v_cvt_pk_bf16_f32 v71, v72, v73
	v_cvt_pk_bf16_f32 v72, v66, v67
	v_cvt_pk_bf16_f32 v73, v68, v69
	global_store_dwordx4 v[86:87], v[70:73], off offset:256
	v_cvt_pk_bf16_f32 v62, v62, v63
	v_cvt_pk_bf16_f32 v63, v64, v65
	v_cvt_pk_bf16_f32 v64, v58, v59
	v_add_co_u32_e32 v58, vcc, s55, v144
	v_lshl_add_u64 v[66:67], v[144:145], 0, s[6:7]
	s_nop 0
	v_addc_co_u32_e32 v59, vcc, 0, v145, vcc
	v_cvt_pk_bf16_f32 v65, v60, v61
	global_store_dwordx4 v[58:59], v[62:65], off
	v_cvt_pk_bf16_f32 v50, v50, v51
	v_cvt_pk_bf16_f32 v51, v52, v53
	v_cvt_pk_bf16_f32 v52, v42, v43
	v_cvt_pk_bf16_f32 v53, v44, v45
	global_store_dwordx4 v[66:67], v[50:53], off offset:256
	v_cvt_pk_bf16_f32 v42, v54, v55
	v_cvt_pk_bf16_f32 v43, v56, v57
	v_cvt_pk_bf16_f32 v44, v46, v47
	v_add_co_u32_e32 v46, vcc, s56, v144
	s_nop 0
	v_lshl_add_u64 v[50:51], v[144:145], 0, s[14:15]
	v_addc_co_u32_e32 v47, vcc, 0, v145, vcc
	v_cvt_pk_bf16_f32 v45, v48, v49
	global_store_dwordx4 v[46:47], v[42:45], off
	v_cvt_pk_bf16_f32 v34, v34, v35
	v_cvt_pk_bf16_f32 v35, v36, v37
	v_cvt_pk_bf16_f32 v36, v26, v27
	v_cvt_pk_bf16_f32 v37, v28, v29
	global_store_dwordx4 v[50:51], v[34:37], off offset:256
	v_cvt_pk_bf16_f32 v26, v38, v39
	v_cvt_pk_bf16_f32 v27, v40, v41
	v_cvt_pk_bf16_f32 v28, v30, v31
	v_add_co_u32_e32 v30, vcc, s57, v144
	s_nop 0
	v_lshl_add_u64 v[34:35], v[144:145], 0, s[16:17]
	v_addc_co_u32_e32 v31, vcc, 0, v145, vcc
	v_cvt_pk_bf16_f32 v29, v32, v33
	global_store_dwordx4 v[30:31], v[26:29], off
	v_cvt_pk_bf16_f32 v18, v18, v19
	v_cvt_pk_bf16_f32 v19, v20, v21
	v_cvt_pk_bf16_f32 v20, v10, v11
	v_cvt_pk_bf16_f32 v21, v12, v13
	global_store_dwordx4 v[34:35], v[18:21], off offset:256
	v_cvt_pk_bf16_f32 v10, v22, v23
	v_cvt_pk_bf16_f32 v11, v24, v25
	v_cvt_pk_bf16_f32 v12, v14, v15
	v_add_co_u32_e32 v14, vcc, s58, v144
	s_nop 0
	v_lshl_add_u64 v[18:19], v[144:145], 0, s[18:19]
	v_addc_co_u32_e32 v15, vcc, 0, v145, vcc
	s_and_b64 vcc, exec, s[4:5]
	v_cvt_pk_bf16_f32 v13, v16, v17
	global_store_dwordx4 v[14:15], v[10:13], off
	v_cvt_pk_bf16_f32 v6, v6, v7
	v_cvt_pk_bf16_f32 v7, v8, v9
	v_cvt_pk_bf16_f32 v8, v2, v3
	v_cvt_pk_bf16_f32 v9, v4, v5
	global_store_dwordx4 v[18:19], v[6:9], off offset:256
	s_cbranch_vccz .LBB0_4126
	s_waitcnt vmcnt(0)
	s_cmpk_gt_u32 s11, 0xff
	s_cbranch_scc1 .LBB0_4137
	s_barrier
